# P0 adaLN GEMV: batch the 40 silu(c) staging loads; attention row-max via permlane32_swap; P10 epilogue pipelined residual loads + gate once per unit
# speedup vs baseline: 1.0133x; 1.0133x over previous
.LBB0_121:
	s_xor_b64 s[34:35], s[36:37], -1
	s_add_i32 s36, s38, s11
	s_ashr_i32 s37, s36, 31
	s_load_dwordx2 s[56:57], s[26:27], 0x30
	s_load_dwordx2 s[58:59], s[26:27], 0x38
	v_lshl_add_u32 v52, s36, 2, v2
	s_waitcnt lgkmcnt(0)
	global_load_dword v64, v52, s[56:57]
	s_add_u32 s56, s56, 0x1000
	s_addc_u32 s57, s57, 0
	global_load_dword v65, v52, s[56:57]
	s_add_u32 s56, s56, 0x1000
	s_addc_u32 s57, s57, 0
	global_load_dword v66, v52, s[56:57]
	s_add_u32 s56, s56, 0x1000
	s_addc_u32 s57, s57, 0
	global_load_dword v67, v52, s[56:57]
	s_add_u32 s56, s56, 0x1000
	s_addc_u32 s57, s57, 0
	global_load_dword v68, v52, s[56:57]
	s_add_u32 s56, s56, 0x1000
	s_addc_u32 s57, s57, 0
	global_load_dword v69, v52, s[56:57]
	s_add_u32 s56, s56, 0x1000
	s_addc_u32 s57, s57, 0
	global_load_dword v70, v52, s[56:57]
	s_add_u32 s56, s56, 0x1000
	s_addc_u32 s57, s57, 0
	global_load_dword v71, v52, s[56:57]
	s_add_u32 s56, s56, 0x1000
	s_addc_u32 s57, s57, 0
	global_load_dword v72, v52, s[56:57]
	s_add_u32 s56, s56, 0x1000
	s_addc_u32 s57, s57, 0
	global_load_dword v73, v52, s[56:57]
	s_add_u32 s56, s56, 0x1000
	s_addc_u32 s57, s57, 0
	global_load_dword v74, v52, s[56:57]
	s_add_u32 s56, s56, 0x1000
	s_addc_u32 s57, s57, 0
	global_load_dword v75, v52, s[56:57]
	s_add_u32 s56, s56, 0x1000
	s_addc_u32 s57, s57, 0
	global_load_dword v76, v52, s[56:57]
	s_add_u32 s56, s56, 0x1000
	s_addc_u32 s57, s57, 0
	global_load_dword v77, v52, s[56:57]
	s_add_u32 s56, s56, 0x1000
	s_addc_u32 s57, s57, 0
	global_load_dword v78, v52, s[56:57]
	s_add_u32 s56, s56, 0x1000
	s_addc_u32 s57, s57, 0
	global_load_dword v79, v52, s[56:57]
	s_add_u32 s56, s56, 0x1000
	s_addc_u32 s57, s57, 0
	global_load_dword v80, v52, s[56:57]
	s_add_u32 s56, s56, 0x1000
	s_addc_u32 s57, s57, 0
	global_load_dword v81, v52, s[56:57]
	s_add_u32 s56, s56, 0x1000
	s_addc_u32 s57, s57, 0
	global_load_dword v82, v52, s[56:57]
	s_add_u32 s56, s56, 0x1000
	s_addc_u32 s57, s57, 0
	global_load_dword v83, v52, s[56:57]
	s_add_u32 s56, s56, 0x1000
	s_addc_u32 s57, s57, 0
	global_load_dword v84, v52, s[56:57]
	s_add_u32 s56, s56, 0x1000
	s_addc_u32 s57, s57, 0
	global_load_dword v85, v52, s[56:57]
	s_add_u32 s56, s56, 0x1000
	s_addc_u32 s57, s57, 0
	global_load_dword v86, v52, s[56:57]
	s_add_u32 s56, s56, 0x1000
	s_addc_u32 s57, s57, 0
	global_load_dword v87, v52, s[56:57]
	s_add_u32 s56, s56, 0x1000
	s_addc_u32 s57, s57, 0
	global_load_dword v88, v52, s[56:57]
	s_add_u32 s56, s56, 0x1000
	s_addc_u32 s57, s57, 0
	global_load_dword v89, v52, s[56:57]
	s_add_u32 s56, s56, 0x1000
	s_addc_u32 s57, s57, 0
	global_load_dword v90, v52, s[56:57]
	s_add_u32 s56, s56, 0x1000
	s_addc_u32 s57, s57, 0
	global_load_dword v91, v52, s[56:57]
	s_add_u32 s56, s56, 0x1000
	s_addc_u32 s57, s57, 0
	global_load_dword v92, v52, s[56:57]
	s_add_u32 s56, s56, 0x1000
	s_addc_u32 s57, s57, 0
	global_load_dword v93, v52, s[56:57]
	s_add_u32 s56, s56, 0x1000
	s_addc_u32 s57, s57, 0
	global_load_dword v94, v52, s[56:57]
	s_add_u32 s56, s56, 0x1000
	s_addc_u32 s57, s57, 0
	global_load_dword v95, v52, s[56:57]
	global_load_dword v96, v52, s[58:59]
	s_add_u32 s58, s58, 0x1000
	s_addc_u32 s59, s59, 0
	global_load_dword v97, v52, s[58:59]
	s_add_u32 s58, s58, 0x1000
	s_addc_u32 s59, s59, 0
	global_load_dword v98, v52, s[58:59]
	s_add_u32 s58, s58, 0x1000
	s_addc_u32 s59, s59, 0
	global_load_dword v99, v52, s[58:59]
	s_add_u32 s58, s58, 0x1000
	s_addc_u32 s59, s59, 0
	global_load_dword v100, v52, s[58:59]
	s_add_u32 s58, s58, 0x1000
	s_addc_u32 s59, s59, 0
	global_load_dword v101, v52, s[58:59]
	s_add_u32 s58, s58, 0x1000
	s_addc_u32 s59, s59, 0
	global_load_dword v102, v52, s[58:59]
	s_add_u32 s58, s58, 0x1000
	s_addc_u32 s59, s59, 0
	global_load_dword v103, v52, s[58:59]
	s_waitcnt vmcnt(39)
	v_mul_f32_e32 v104, 0xbfb8aa3b, v64
	v_exp_f32_e32 v104, v104
	s_nop 0
	v_add_f32_e32 v104, 1.0, v104
	v_div_scale_f32 v105, s[54:55], v104, v104, v64
	v_rcp_f32_e32 v106, v105
	v_div_scale_f32 v107, vcc, v64, v104, v64
	v_fma_f32 v108, -v105, v106, 1.0
	v_fmac_f32_e32 v106, v108, v106
	v_mul_f32_e32 v108, v107, v106
	v_fma_f32 v109, -v105, v108, v107
	v_fmac_f32_e32 v108, v109, v106
	v_fma_f32 v105, -v105, v108, v107
	v_div_fmas_f32 v105, v105, v106, v108
	v_div_fixup_f32 v64, v105, v104, v64
	ds_write_b32 v1, v64
	s_waitcnt vmcnt(38)
	v_mul_f32_e32 v104, 0xbfb8aa3b, v65
	v_exp_f32_e32 v104, v104
	s_nop 0
	v_add_f32_e32 v104, 1.0, v104
	v_div_scale_f32 v105, s[54:55], v104, v104, v65
	v_rcp_f32_e32 v106, v105
	v_div_scale_f32 v107, vcc, v65, v104, v65
	v_fma_f32 v108, -v105, v106, 1.0
	v_fmac_f32_e32 v106, v108, v106
	v_mul_f32_e32 v108, v107, v106
	v_fma_f32 v109, -v105, v108, v107
	v_fmac_f32_e32 v108, v109, v106
	v_fma_f32 v105, -v105, v108, v107
	v_div_fmas_f32 v105, v105, v106, v108
	v_div_fixup_f32 v65, v105, v104, v65
	ds_write_b32 v1, v65 offset:256
	s_waitcnt vmcnt(37)
	v_mul_f32_e32 v104, 0xbfb8aa3b, v66
	v_exp_f32_e32 v104, v104
	s_nop 0
	v_add_f32_e32 v104, 1.0, v104
	v_div_scale_f32 v105, s[54:55], v104, v104, v66
	v_rcp_f32_e32 v106, v105
	v_div_scale_f32 v107, vcc, v66, v104, v66
	v_fma_f32 v108, -v105, v106, 1.0
	v_fmac_f32_e32 v106, v108, v106
	v_mul_f32_e32 v108, v107, v106
	v_fma_f32 v109, -v105, v108, v107
	v_fmac_f32_e32 v108, v109, v106
	v_fma_f32 v105, -v105, v108, v107
	v_div_fmas_f32 v105, v105, v106, v108
	v_div_fixup_f32 v66, v105, v104, v66
	ds_write_b32 v1, v66 offset:512
	s_waitcnt vmcnt(36)
	v_mul_f32_e32 v104, 0xbfb8aa3b, v67
	v_exp_f32_e32 v104, v104
	s_nop 0
	v_add_f32_e32 v104, 1.0, v104
	v_div_scale_f32 v105, s[54:55], v104, v104, v67
	v_rcp_f32_e32 v106, v105
	v_div_scale_f32 v107, vcc, v67, v104, v67
	v_fma_f32 v108, -v105, v106, 1.0
	v_fmac_f32_e32 v106, v108, v106
	v_mul_f32_e32 v108, v107, v106
	v_fma_f32 v109, -v105, v108, v107
	v_fmac_f32_e32 v108, v109, v106
	v_fma_f32 v105, -v105, v108, v107
	v_div_fmas_f32 v105, v105, v106, v108
	v_div_fixup_f32 v67, v105, v104, v67
	ds_write_b32 v1, v67 offset:768
	s_waitcnt vmcnt(35)
	v_mul_f32_e32 v104, 0xbfb8aa3b, v68
	v_exp_f32_e32 v104, v104
	s_nop 0
	v_add_f32_e32 v104, 1.0, v104
	v_div_scale_f32 v105, s[54:55], v104, v104, v68
	v_rcp_f32_e32 v106, v105
	v_div_scale_f32 v107, vcc, v68, v104, v68
	v_fma_f32 v108, -v105, v106, 1.0
	v_fmac_f32_e32 v106, v108, v106
	v_mul_f32_e32 v108, v107, v106
	v_fma_f32 v109, -v105, v108, v107
	v_fmac_f32_e32 v108, v109, v106
	v_fma_f32 v105, -v105, v108, v107
	v_div_fmas_f32 v105, v105, v106, v108
	v_div_fixup_f32 v68, v105, v104, v68
	ds_write_b32 v1, v68 offset:1024
	s_waitcnt vmcnt(34)
	v_mul_f32_e32 v104, 0xbfb8aa3b, v69
	v_exp_f32_e32 v104, v104
	s_nop 0
	v_add_f32_e32 v104, 1.0, v104
	v_div_scale_f32 v105, s[54:55], v104, v104, v69
	v_rcp_f32_e32 v106, v105
	v_div_scale_f32 v107, vcc, v69, v104, v69
	v_fma_f32 v108, -v105, v106, 1.0
	v_fmac_f32_e32 v106, v108, v106
	v_mul_f32_e32 v108, v107, v106
	v_fma_f32 v109, -v105, v108, v107
	v_fmac_f32_e32 v108, v109, v106
	v_fma_f32 v105, -v105, v108, v107
	v_div_fmas_f32 v105, v105, v106, v108
	v_div_fixup_f32 v69, v105, v104, v69
	ds_write_b32 v1, v69 offset:1280
	s_waitcnt vmcnt(33)
	v_mul_f32_e32 v104, 0xbfb8aa3b, v70
	v_exp_f32_e32 v104, v104
	s_nop 0
	v_add_f32_e32 v104, 1.0, v104
	v_div_scale_f32 v105, s[54:55], v104, v104, v70
	v_rcp_f32_e32 v106, v105
	v_div_scale_f32 v107, vcc, v70, v104, v70
	v_fma_f32 v108, -v105, v106, 1.0
	v_fmac_f32_e32 v106, v108, v106
	v_mul_f32_e32 v108, v107, v106
	v_fma_f32 v109, -v105, v108, v107
	v_fmac_f32_e32 v108, v109, v106
	v_fma_f32 v105, -v105, v108, v107
	v_div_fmas_f32 v105, v105, v106, v108
	v_div_fixup_f32 v70, v105, v104, v70
	ds_write_b32 v1, v70 offset:1536
	s_waitcnt vmcnt(32)
	v_mul_f32_e32 v104, 0xbfb8aa3b, v71
	v_exp_f32_e32 v104, v104
	s_nop 0
	v_add_f32_e32 v104, 1.0, v104
	v_div_scale_f32 v105, s[54:55], v104, v104, v71
	v_rcp_f32_e32 v106, v105
	v_div_scale_f32 v107, vcc, v71, v104, v71
	v_fma_f32 v108, -v105, v106, 1.0
	v_fmac_f32_e32 v106, v108, v106
	v_mul_f32_e32 v108, v107, v106
	v_fma_f32 v109, -v105, v108, v107
	v_fmac_f32_e32 v108, v109, v106
	v_fma_f32 v105, -v105, v108, v107
	v_div_fmas_f32 v105, v105, v106, v108
	v_div_fixup_f32 v71, v105, v104, v71
	ds_write_b32 v1, v71 offset:1792
	s_waitcnt vmcnt(31)
	v_mul_f32_e32 v104, 0xbfb8aa3b, v72
	v_exp_f32_e32 v104, v104
	s_nop 0
	v_add_f32_e32 v104, 1.0, v104
	v_div_scale_f32 v105, s[54:55], v104, v104, v72
	v_rcp_f32_e32 v106, v105
	v_div_scale_f32 v107, vcc, v72, v104, v72
	v_fma_f32 v108, -v105, v106, 1.0
	v_fmac_f32_e32 v106, v108, v106
	v_mul_f32_e32 v108, v107, v106
	v_fma_f32 v109, -v105, v108, v107
	v_fmac_f32_e32 v108, v109, v106
	v_fma_f32 v105, -v105, v108, v107
	v_div_fmas_f32 v105, v105, v106, v108
	v_div_fixup_f32 v72, v105, v104, v72
	ds_write_b32 v1, v72 offset:2048
	s_waitcnt vmcnt(30)
	v_mul_f32_e32 v104, 0xbfb8aa3b, v73
	v_exp_f32_e32 v104, v104
	s_nop 0
	v_add_f32_e32 v104, 1.0, v104
	v_div_scale_f32 v105, s[54:55], v104, v104, v73
	v_rcp_f32_e32 v106, v105
	v_div_scale_f32 v107, vcc, v73, v104, v73
	v_fma_f32 v108, -v105, v106, 1.0
	v_fmac_f32_e32 v106, v108, v106
	v_mul_f32_e32 v108, v107, v106
	v_fma_f32 v109, -v105, v108, v107
	v_fmac_f32_e32 v108, v109, v106
	v_fma_f32 v105, -v105, v108, v107
	v_div_fmas_f32 v105, v105, v106, v108
	v_div_fixup_f32 v73, v105, v104, v73
	ds_write_b32 v1, v73 offset:2304
	s_waitcnt vmcnt(29)
	v_mul_f32_e32 v104, 0xbfb8aa3b, v74
	v_exp_f32_e32 v104, v104
	s_nop 0
	v_add_f32_e32 v104, 1.0, v104
	v_div_scale_f32 v105, s[54:55], v104, v104, v74
	v_rcp_f32_e32 v106, v105
	v_div_scale_f32 v107, vcc, v74, v104, v74
	v_fma_f32 v108, -v105, v106, 1.0
	v_fmac_f32_e32 v106, v108, v106
	v_mul_f32_e32 v108, v107, v106
	v_fma_f32 v109, -v105, v108, v107
	v_fmac_f32_e32 v108, v109, v106
	v_fma_f32 v105, -v105, v108, v107
	v_div_fmas_f32 v105, v105, v106, v108
	v_div_fixup_f32 v74, v105, v104, v74
	ds_write_b32 v1, v74 offset:2560
	s_waitcnt vmcnt(28)
	v_mul_f32_e32 v104, 0xbfb8aa3b, v75
	v_exp_f32_e32 v104, v104
	s_nop 0
	v_add_f32_e32 v104, 1.0, v104
	v_div_scale_f32 v105, s[54:55], v104, v104, v75
	v_rcp_f32_e32 v106, v105
	v_div_scale_f32 v107, vcc, v75, v104, v75
	v_fma_f32 v108, -v105, v106, 1.0
	v_fmac_f32_e32 v106, v108, v106
	v_mul_f32_e32 v108, v107, v106
	v_fma_f32 v109, -v105, v108, v107
	v_fmac_f32_e32 v108, v109, v106
	v_fma_f32 v105, -v105, v108, v107
	v_div_fmas_f32 v105, v105, v106, v108
	v_div_fixup_f32 v75, v105, v104, v75
	ds_write_b32 v1, v75 offset:2816
	s_waitcnt vmcnt(27)
	v_mul_f32_e32 v104, 0xbfb8aa3b, v76
	v_exp_f32_e32 v104, v104
	s_nop 0
	v_add_f32_e32 v104, 1.0, v104
	v_div_scale_f32 v105, s[54:55], v104, v104, v76
	v_rcp_f32_e32 v106, v105
	v_div_scale_f32 v107, vcc, v76, v104, v76
	v_fma_f32 v108, -v105, v106, 1.0
	v_fmac_f32_e32 v106, v108, v106
	v_mul_f32_e32 v108, v107, v106
	v_fma_f32 v109, -v105, v108, v107
	v_fmac_f32_e32 v108, v109, v106
	v_fma_f32 v105, -v105, v108, v107
	v_div_fmas_f32 v105, v105, v106, v108
	v_div_fixup_f32 v76, v105, v104, v76
	ds_write_b32 v1, v76 offset:3072
	s_waitcnt vmcnt(26)
	v_mul_f32_e32 v104, 0xbfb8aa3b, v77
	v_exp_f32_e32 v104, v104
	s_nop 0
	v_add_f32_e32 v104, 1.0, v104
	v_div_scale_f32 v105, s[54:55], v104, v104, v77
	v_rcp_f32_e32 v106, v105
	v_div_scale_f32 v107, vcc, v77, v104, v77
	v_fma_f32 v108, -v105, v106, 1.0
	v_fmac_f32_e32 v106, v108, v106
	v_mul_f32_e32 v108, v107, v106
	v_fma_f32 v109, -v105, v108, v107
	v_fmac_f32_e32 v108, v109, v106
	v_fma_f32 v105, -v105, v108, v107
	v_div_fmas_f32 v105, v105, v106, v108
	v_div_fixup_f32 v77, v105, v104, v77
	ds_write_b32 v1, v77 offset:3328
	s_waitcnt vmcnt(25)
	v_mul_f32_e32 v104, 0xbfb8aa3b, v78
	v_exp_f32_e32 v104, v104
	s_nop 0
	v_add_f32_e32 v104, 1.0, v104
	v_div_scale_f32 v105, s[54:55], v104, v104, v78
	v_rcp_f32_e32 v106, v105
	v_div_scale_f32 v107, vcc, v78, v104, v78
	v_fma_f32 v108, -v105, v106, 1.0
	v_fmac_f32_e32 v106, v108, v106
	v_mul_f32_e32 v108, v107, v106
	v_fma_f32 v109, -v105, v108, v107
	v_fmac_f32_e32 v108, v109, v106
	v_fma_f32 v105, -v105, v108, v107
	v_div_fmas_f32 v105, v105, v106, v108
	v_div_fixup_f32 v78, v105, v104, v78
	ds_write_b32 v1, v78 offset:3584
	s_waitcnt vmcnt(24)
	v_mul_f32_e32 v104, 0xbfb8aa3b, v79
	v_exp_f32_e32 v104, v104
	s_nop 0
	v_add_f32_e32 v104, 1.0, v104
	v_div_scale_f32 v105, s[54:55], v104, v104, v79
	v_rcp_f32_e32 v106, v105
	v_div_scale_f32 v107, vcc, v79, v104, v79
	v_fma_f32 v108, -v105, v106, 1.0
	v_fmac_f32_e32 v106, v108, v106
	v_mul_f32_e32 v108, v107, v106
	v_fma_f32 v109, -v105, v108, v107
	v_fmac_f32_e32 v108, v109, v106
	v_fma_f32 v105, -v105, v108, v107
	v_div_fmas_f32 v105, v105, v106, v108
	v_div_fixup_f32 v79, v105, v104, v79
	ds_write_b32 v1, v79 offset:3840
	s_waitcnt vmcnt(23)
	v_mul_f32_e32 v104, 0xbfb8aa3b, v80
	v_exp_f32_e32 v104, v104
	s_nop 0
	v_add_f32_e32 v104, 1.0, v104
	v_div_scale_f32 v105, s[54:55], v104, v104, v80
	v_rcp_f32_e32 v106, v105
	v_div_scale_f32 v107, vcc, v80, v104, v80
	v_fma_f32 v108, -v105, v106, 1.0
	v_fmac_f32_e32 v106, v108, v106
	v_mul_f32_e32 v108, v107, v106
	v_fma_f32 v109, -v105, v108, v107
	v_fmac_f32_e32 v108, v109, v106
	v_fma_f32 v105, -v105, v108, v107
	v_div_fmas_f32 v105, v105, v106, v108
	v_div_fixup_f32 v80, v105, v104, v80
	ds_write_b32 v1, v80 offset:4096
	s_waitcnt vmcnt(22)
	v_mul_f32_e32 v104, 0xbfb8aa3b, v81
	v_exp_f32_e32 v104, v104
	s_nop 0
	v_add_f32_e32 v104, 1.0, v104
	v_div_scale_f32 v105, s[54:55], v104, v104, v81
	v_rcp_f32_e32 v106, v105
	v_div_scale_f32 v107, vcc, v81, v104, v81
	v_fma_f32 v108, -v105, v106, 1.0
	v_fmac_f32_e32 v106, v108, v106
	v_mul_f32_e32 v108, v107, v106
	v_fma_f32 v109, -v105, v108, v107
	v_fmac_f32_e32 v108, v109, v106
	v_fma_f32 v105, -v105, v108, v107
	v_div_fmas_f32 v105, v105, v106, v108
	v_div_fixup_f32 v81, v105, v104, v81
	ds_write_b32 v1, v81 offset:4352
	s_waitcnt vmcnt(21)
	v_mul_f32_e32 v104, 0xbfb8aa3b, v82
	v_exp_f32_e32 v104, v104
	s_nop 0
	v_add_f32_e32 v104, 1.0, v104
	v_div_scale_f32 v105, s[54:55], v104, v104, v82
	v_rcp_f32_e32 v106, v105
	v_div_scale_f32 v107, vcc, v82, v104, v82
	v_fma_f32 v108, -v105, v106, 1.0
	v_fmac_f32_e32 v106, v108, v106
	v_mul_f32_e32 v108, v107, v106
	v_fma_f32 v109, -v105, v108, v107
	v_fmac_f32_e32 v108, v109, v106
	v_fma_f32 v105, -v105, v108, v107
	v_div_fmas_f32 v105, v105, v106, v108
	v_div_fixup_f32 v82, v105, v104, v82
	ds_write_b32 v1, v82 offset:4608
	s_waitcnt vmcnt(20)
	v_mul_f32_e32 v104, 0xbfb8aa3b, v83
	v_exp_f32_e32 v104, v104
	s_nop 0
	v_add_f32_e32 v104, 1.0, v104
	v_div_scale_f32 v105, s[54:55], v104, v104, v83
	v_rcp_f32_e32 v106, v105
	v_div_scale_f32 v107, vcc, v83, v104, v83
	v_fma_f32 v108, -v105, v106, 1.0
	v_fmac_f32_e32 v106, v108, v106
	v_mul_f32_e32 v108, v107, v106
	v_fma_f32 v109, -v105, v108, v107
	v_fmac_f32_e32 v108, v109, v106
	v_fma_f32 v105, -v105, v108, v107
	v_div_fmas_f32 v105, v105, v106, v108
	v_div_fixup_f32 v83, v105, v104, v83
	ds_write_b32 v1, v83 offset:4864
	s_waitcnt vmcnt(19)
	v_mul_f32_e32 v104, 0xbfb8aa3b, v84
	v_exp_f32_e32 v104, v104
	s_nop 0
	v_add_f32_e32 v104, 1.0, v104
	v_div_scale_f32 v105, s[54:55], v104, v104, v84
	v_rcp_f32_e32 v106, v105
	v_div_scale_f32 v107, vcc, v84, v104, v84
	v_fma_f32 v108, -v105, v106, 1.0
	v_fmac_f32_e32 v106, v108, v106
	v_mul_f32_e32 v108, v107, v106
	v_fma_f32 v109, -v105, v108, v107
	v_fmac_f32_e32 v108, v109, v106
	v_fma_f32 v105, -v105, v108, v107
	v_div_fmas_f32 v105, v105, v106, v108
	v_div_fixup_f32 v84, v105, v104, v84
	ds_write_b32 v1, v84 offset:5120
	s_waitcnt vmcnt(18)
	v_mul_f32_e32 v104, 0xbfb8aa3b, v85
	v_exp_f32_e32 v104, v104
	s_nop 0
	v_add_f32_e32 v104, 1.0, v104
	v_div_scale_f32 v105, s[54:55], v104, v104, v85
	v_rcp_f32_e32 v106, v105
	v_div_scale_f32 v107, vcc, v85, v104, v85
	v_fma_f32 v108, -v105, v106, 1.0
	v_fmac_f32_e32 v106, v108, v106
	v_mul_f32_e32 v108, v107, v106
	v_fma_f32 v109, -v105, v108, v107
	v_fmac_f32_e32 v108, v109, v106
	v_fma_f32 v105, -v105, v108, v107
	v_div_fmas_f32 v105, v105, v106, v108
	v_div_fixup_f32 v85, v105, v104, v85
	ds_write_b32 v1, v85 offset:5376
	s_waitcnt vmcnt(17)
	v_mul_f32_e32 v104, 0xbfb8aa3b, v86
	v_exp_f32_e32 v104, v104
	s_nop 0
	v_add_f32_e32 v104, 1.0, v104
	v_div_scale_f32 v105, s[54:55], v104, v104, v86
	v_rcp_f32_e32 v106, v105
	v_div_scale_f32 v107, vcc, v86, v104, v86
	v_fma_f32 v108, -v105, v106, 1.0
	v_fmac_f32_e32 v106, v108, v106
	v_mul_f32_e32 v108, v107, v106
	v_fma_f32 v109, -v105, v108, v107
	v_fmac_f32_e32 v108, v109, v106
	v_fma_f32 v105, -v105, v108, v107
	v_div_fmas_f32 v105, v105, v106, v108
	v_div_fixup_f32 v86, v105, v104, v86
	ds_write_b32 v1, v86 offset:5632
	s_waitcnt vmcnt(16)
	v_mul_f32_e32 v104, 0xbfb8aa3b, v87
	v_exp_f32_e32 v104, v104
	s_nop 0
	v_add_f32_e32 v104, 1.0, v104
	v_div_scale_f32 v105, s[54:55], v104, v104, v87
	v_rcp_f32_e32 v106, v105
	v_div_scale_f32 v107, vcc, v87, v104, v87
	v_fma_f32 v108, -v105, v106, 1.0
	v_fmac_f32_e32 v106, v108, v106
	v_mul_f32_e32 v108, v107, v106
	v_fma_f32 v109, -v105, v108, v107
	v_fmac_f32_e32 v108, v109, v106
	v_fma_f32 v105, -v105, v108, v107
	v_div_fmas_f32 v105, v105, v106, v108
	v_div_fixup_f32 v87, v105, v104, v87
	ds_write_b32 v1, v87 offset:5888
	s_waitcnt vmcnt(15)
	v_mul_f32_e32 v104, 0xbfb8aa3b, v88
	v_exp_f32_e32 v104, v104
	s_nop 0
	v_add_f32_e32 v104, 1.0, v104
	v_div_scale_f32 v105, s[54:55], v104, v104, v88
	v_rcp_f32_e32 v106, v105
	v_div_scale_f32 v107, vcc, v88, v104, v88
	v_fma_f32 v108, -v105, v106, 1.0
	v_fmac_f32_e32 v106, v108, v106
	v_mul_f32_e32 v108, v107, v106
	v_fma_f32 v109, -v105, v108, v107
	v_fmac_f32_e32 v108, v109, v106
	v_fma_f32 v105, -v105, v108, v107
	v_div_fmas_f32 v105, v105, v106, v108
	v_div_fixup_f32 v88, v105, v104, v88
	ds_write_b32 v1, v88 offset:6144
	s_waitcnt vmcnt(14)
	v_mul_f32_e32 v104, 0xbfb8aa3b, v89
	v_exp_f32_e32 v104, v104
	s_nop 0
	v_add_f32_e32 v104, 1.0, v104
	v_div_scale_f32 v105, s[54:55], v104, v104, v89
	v_rcp_f32_e32 v106, v105
	v_div_scale_f32 v107, vcc, v89, v104, v89
	v_fma_f32 v108, -v105, v106, 1.0
	v_fmac_f32_e32 v106, v108, v106
	v_mul_f32_e32 v108, v107, v106
	v_fma_f32 v109, -v105, v108, v107
	v_fmac_f32_e32 v108, v109, v106
	v_fma_f32 v105, -v105, v108, v107
	v_div_fmas_f32 v105, v105, v106, v108
	v_div_fixup_f32 v89, v105, v104, v89
	ds_write_b32 v1, v89 offset:6400
	s_waitcnt vmcnt(13)
	v_mul_f32_e32 v104, 0xbfb8aa3b, v90
	v_exp_f32_e32 v104, v104
	s_nop 0
	v_add_f32_e32 v104, 1.0, v104
	v_div_scale_f32 v105, s[54:55], v104, v104, v90
	v_rcp_f32_e32 v106, v105
	v_div_scale_f32 v107, vcc, v90, v104, v90
	v_fma_f32 v108, -v105, v106, 1.0
	v_fmac_f32_e32 v106, v108, v106
	v_mul_f32_e32 v108, v107, v106
	v_fma_f32 v109, -v105, v108, v107
	v_fmac_f32_e32 v108, v109, v106
	v_fma_f32 v105, -v105, v108, v107
	v_div_fmas_f32 v105, v105, v106, v108
	v_div_fixup_f32 v90, v105, v104, v90
	ds_write_b32 v1, v90 offset:6656
	s_waitcnt vmcnt(12)
	v_mul_f32_e32 v104, 0xbfb8aa3b, v91
	v_exp_f32_e32 v104, v104
	s_nop 0
	v_add_f32_e32 v104, 1.0, v104
	v_div_scale_f32 v105, s[54:55], v104, v104, v91
	v_rcp_f32_e32 v106, v105
	v_div_scale_f32 v107, vcc, v91, v104, v91
	v_fma_f32 v108, -v105, v106, 1.0
	v_fmac_f32_e32 v106, v108, v106
	v_mul_f32_e32 v108, v107, v106
	v_fma_f32 v109, -v105, v108, v107
	v_fmac_f32_e32 v108, v109, v106
	v_fma_f32 v105, -v105, v108, v107
	v_div_fmas_f32 v105, v105, v106, v108
	v_div_fixup_f32 v91, v105, v104, v91
	ds_write_b32 v1, v91 offset:6912
	s_waitcnt vmcnt(11)
	v_mul_f32_e32 v104, 0xbfb8aa3b, v92
	v_exp_f32_e32 v104, v104
	s_nop 0
	v_add_f32_e32 v104, 1.0, v104
	v_div_scale_f32 v105, s[54:55], v104, v104, v92
	v_rcp_f32_e32 v106, v105
	v_div_scale_f32 v107, vcc, v92, v104, v92
	v_fma_f32 v108, -v105, v106, 1.0
	v_fmac_f32_e32 v106, v108, v106
	v_mul_f32_e32 v108, v107, v106
	v_fma_f32 v109, -v105, v108, v107
	v_fmac_f32_e32 v108, v109, v106
	v_fma_f32 v105, -v105, v108, v107
	v_div_fmas_f32 v105, v105, v106, v108
	v_div_fixup_f32 v92, v105, v104, v92
	ds_write_b32 v1, v92 offset:7168
	s_waitcnt vmcnt(10)
	v_mul_f32_e32 v104, 0xbfb8aa3b, v93
	v_exp_f32_e32 v104, v104
	s_nop 0
	v_add_f32_e32 v104, 1.0, v104
	v_div_scale_f32 v105, s[54:55], v104, v104, v93
	v_rcp_f32_e32 v106, v105
	v_div_scale_f32 v107, vcc, v93, v104, v93
	v_fma_f32 v108, -v105, v106, 1.0
	v_fmac_f32_e32 v106, v108, v106
	v_mul_f32_e32 v108, v107, v106
	v_fma_f32 v109, -v105, v108, v107
	v_fmac_f32_e32 v108, v109, v106
	v_fma_f32 v105, -v105, v108, v107
	v_div_fmas_f32 v105, v105, v106, v108
	v_div_fixup_f32 v93, v105, v104, v93
	ds_write_b32 v1, v93 offset:7424
	s_waitcnt vmcnt(9)
	v_mul_f32_e32 v104, 0xbfb8aa3b, v94
	v_exp_f32_e32 v104, v104
	s_nop 0
	v_add_f32_e32 v104, 1.0, v104
	v_div_scale_f32 v105, s[54:55], v104, v104, v94
	v_rcp_f32_e32 v106, v105
	v_div_scale_f32 v107, vcc, v94, v104, v94
	v_fma_f32 v108, -v105, v106, 1.0
	v_fmac_f32_e32 v106, v108, v106
	v_mul_f32_e32 v108, v107, v106
	v_fma_f32 v109, -v105, v108, v107
	v_fmac_f32_e32 v108, v109, v106
	v_fma_f32 v105, -v105, v108, v107
	v_div_fmas_f32 v105, v105, v106, v108
	v_div_fixup_f32 v94, v105, v104, v94
	ds_write_b32 v1, v94 offset:7680
	s_waitcnt vmcnt(8)
	v_mul_f32_e32 v104, 0xbfb8aa3b, v95
	v_exp_f32_e32 v104, v104
	s_nop 0
	v_add_f32_e32 v104, 1.0, v104
	v_div_scale_f32 v105, s[54:55], v104, v104, v95
	v_rcp_f32_e32 v106, v105
	v_div_scale_f32 v107, vcc, v95, v104, v95
	v_fma_f32 v108, -v105, v106, 1.0
	v_fmac_f32_e32 v106, v108, v106
	v_mul_f32_e32 v108, v107, v106
	v_fma_f32 v109, -v105, v108, v107
	v_fmac_f32_e32 v108, v109, v106
	v_fma_f32 v105, -v105, v108, v107
	v_div_fmas_f32 v105, v105, v106, v108
	v_div_fixup_f32 v95, v105, v104, v95
	ds_write_b32 v1, v95 offset:7936
	s_waitcnt vmcnt(7)
	v_mul_f32_e32 v104, 0xbfb8aa3b, v96
	v_exp_f32_e32 v104, v104
	s_nop 0
	v_add_f32_e32 v104, 1.0, v104
	v_div_scale_f32 v105, s[54:55], v104, v104, v96
	v_rcp_f32_e32 v106, v105
	v_div_scale_f32 v107, vcc, v96, v104, v96
	v_fma_f32 v108, -v105, v106, 1.0
	v_fmac_f32_e32 v106, v108, v106
	v_mul_f32_e32 v108, v107, v106
	v_fma_f32 v109, -v105, v108, v107
	v_fmac_f32_e32 v108, v109, v106
	v_fma_f32 v105, -v105, v108, v107
	v_div_fmas_f32 v105, v105, v106, v108
	v_div_fixup_f32 v96, v105, v104, v96
	ds_write_b32 v1, v96 offset:8192
	s_waitcnt vmcnt(6)
	v_mul_f32_e32 v104, 0xbfb8aa3b, v97
	v_exp_f32_e32 v104, v104
	s_nop 0
	v_add_f32_e32 v104, 1.0, v104
	v_div_scale_f32 v105, s[54:55], v104, v104, v97
	v_rcp_f32_e32 v106, v105
	v_div_scale_f32 v107, vcc, v97, v104, v97
	v_fma_f32 v108, -v105, v106, 1.0
	v_fmac_f32_e32 v106, v108, v106
	v_mul_f32_e32 v108, v107, v106
	v_fma_f32 v109, -v105, v108, v107
	v_fmac_f32_e32 v108, v109, v106
	v_fma_f32 v105, -v105, v108, v107
	v_div_fmas_f32 v105, v105, v106, v108
	v_div_fixup_f32 v97, v105, v104, v97
	ds_write_b32 v1, v97 offset:8448
	s_waitcnt vmcnt(5)
	v_mul_f32_e32 v104, 0xbfb8aa3b, v98
	v_exp_f32_e32 v104, v104
	s_nop 0
	v_add_f32_e32 v104, 1.0, v104
	v_div_scale_f32 v105, s[54:55], v104, v104, v98
	v_rcp_f32_e32 v106, v105
	v_div_scale_f32 v107, vcc, v98, v104, v98
	v_fma_f32 v108, -v105, v106, 1.0
	v_fmac_f32_e32 v106, v108, v106
	v_mul_f32_e32 v108, v107, v106
	v_fma_f32 v109, -v105, v108, v107
	v_fmac_f32_e32 v108, v109, v106
	v_fma_f32 v105, -v105, v108, v107
	v_div_fmas_f32 v105, v105, v106, v108
	v_div_fixup_f32 v98, v105, v104, v98
	ds_write_b32 v1, v98 offset:8704
	s_waitcnt vmcnt(4)
	v_mul_f32_e32 v104, 0xbfb8aa3b, v99
	v_exp_f32_e32 v104, v104
	s_nop 0
	v_add_f32_e32 v104, 1.0, v104
	v_div_scale_f32 v105, s[54:55], v104, v104, v99
	v_rcp_f32_e32 v106, v105
	v_div_scale_f32 v107, vcc, v99, v104, v99
	v_fma_f32 v108, -v105, v106, 1.0
	v_fmac_f32_e32 v106, v108, v106
	v_mul_f32_e32 v108, v107, v106
	v_fma_f32 v109, -v105, v108, v107
	v_fmac_f32_e32 v108, v109, v106
	v_fma_f32 v105, -v105, v108, v107
	v_div_fmas_f32 v105, v105, v106, v108
	v_div_fixup_f32 v99, v105, v104, v99
	ds_write_b32 v1, v99 offset:8960
	s_waitcnt vmcnt(3)
	v_mul_f32_e32 v104, 0xbfb8aa3b, v100
	v_exp_f32_e32 v104, v104
	s_nop 0
	v_add_f32_e32 v104, 1.0, v104
	v_div_scale_f32 v105, s[54:55], v104, v104, v100
	v_rcp_f32_e32 v106, v105
	v_div_scale_f32 v107, vcc, v100, v104, v100
	v_fma_f32 v108, -v105, v106, 1.0
	v_fmac_f32_e32 v106, v108, v106
	v_mul_f32_e32 v108, v107, v106
	v_fma_f32 v109, -v105, v108, v107
	v_fmac_f32_e32 v108, v109, v106
	v_fma_f32 v105, -v105, v108, v107
	v_div_fmas_f32 v105, v105, v106, v108
	v_div_fixup_f32 v100, v105, v104, v100
	ds_write_b32 v1, v100 offset:9216
	s_waitcnt vmcnt(2)
	v_mul_f32_e32 v104, 0xbfb8aa3b, v101
	v_exp_f32_e32 v104, v104
	s_nop 0
	v_add_f32_e32 v104, 1.0, v104
	v_div_scale_f32 v105, s[54:55], v104, v104, v101
	v_rcp_f32_e32 v106, v105
	v_div_scale_f32 v107, vcc, v101, v104, v101
	v_fma_f32 v108, -v105, v106, 1.0
	v_fmac_f32_e32 v106, v108, v106
	v_mul_f32_e32 v108, v107, v106
	v_fma_f32 v109, -v105, v108, v107
	v_fmac_f32_e32 v108, v109, v106
	v_fma_f32 v105, -v105, v108, v107
	v_div_fmas_f32 v105, v105, v106, v108
	v_div_fixup_f32 v101, v105, v104, v101
	ds_write_b32 v1, v101 offset:9472
	s_waitcnt vmcnt(1)
	v_mul_f32_e32 v104, 0xbfb8aa3b, v102
	v_exp_f32_e32 v104, v104
	s_nop 0
	v_add_f32_e32 v104, 1.0, v104
	v_div_scale_f32 v105, s[54:55], v104, v104, v102
	v_rcp_f32_e32 v106, v105
	v_div_scale_f32 v107, vcc, v102, v104, v102
	v_fma_f32 v108, -v105, v106, 1.0
	v_fmac_f32_e32 v106, v108, v106
	v_mul_f32_e32 v108, v107, v106
	v_fma_f32 v109, -v105, v108, v107
	v_fmac_f32_e32 v108, v109, v106
	v_fma_f32 v105, -v105, v108, v107
	v_div_fmas_f32 v105, v105, v106, v108
	v_div_fixup_f32 v102, v105, v104, v102
	ds_write_b32 v1, v102 offset:9728
	s_waitcnt vmcnt(0)
	v_mul_f32_e32 v104, 0xbfb8aa3b, v103
	v_exp_f32_e32 v104, v104
	s_nop 0
	v_add_f32_e32 v104, 1.0, v104
	v_div_scale_f32 v105, s[54:55], v104, v104, v103
	v_rcp_f32_e32 v106, v105
	v_div_scale_f32 v107, vcc, v103, v104, v103
	v_fma_f32 v108, -v105, v106, 1.0
	v_fmac_f32_e32 v106, v108, v106
	v_mul_f32_e32 v108, v107, v106
	v_fma_f32 v109, -v105, v108, v107
	v_fmac_f32_e32 v108, v109, v106
	v_fma_f32 v105, -v105, v108, v107
	v_div_fmas_f32 v105, v105, v106, v108
	v_div_fixup_f32 v103, v105, v104, v103
	ds_write_b32 v1, v103 offset:9984
	s_waitcnt lgkmcnt(0)
	s_load_dwordx2 s[38:39], s[26:27], 0x48
	s_mov_b32 s37, -4
	s_waitcnt lgkmcnt(0)
	v_lshl_add_u64 v[48:49], s[38:39], 0, v[4:5]
	v_lshl_add_u64 v[48:49], v[48:49], 0, s[30:31]
	v_mad_i64_i32 v[48:49], s[38:39], s36, v62, v[48:49]
	s_mov_b32 s36, s9

.LBB0_560:
	s_waitcnt lgkmcnt(6)
	v_mfma_f32_32x32x16_bf16 v[48:63], v[152:155], v[136:139], v[48:63]
	s_xor_b64 s[44:45], s[44:45], -1
	s_waitcnt lgkmcnt(2)
	v_mfma_f32_32x32x16_bf16 v[32:47], v[156:159], v[136:139], v[32:47]
	v_mfma_f32_32x32x16_bf16 v[48:63], v[74:77], v[132:135], v[48:63]
	s_waitcnt lgkmcnt(1)
	v_mfma_f32_32x32x16_bf16 v[32:47], v[144:147], v[132:135], v[32:47]
	v_mfma_f32_32x32x16_bf16 v[48:63], v[70:73], v[128:131], v[48:63]
	ds_read_b128 v[12:15], v192 offset:9216
	ds_read_b128 v[74:77], v192 offset:9248
	ds_read_b128 v[28:31], v192 offset:9280
	ds_read_b128 v[20:23], v192 offset:9312
	ds_read_b128 v[144:147], v192 offset:13824
	ds_read_b128 v[70:73], v192 offset:13856
	ds_read_b128 v[24:27], v192 offset:13888
	ds_read_b128 v[16:19], v192 offset:13920
	s_waitcnt lgkmcnt(8)
	v_mfma_f32_32x32x16_bf16 v[32:47], v[148:151], v[128:131], v[32:47]
	s_nop 1
	v_max_f32_e32 v0, v49, v49
	v_max_f32_e32 v1, v48, v48
	v_max_f32_e32 v0, v1, v0
	v_max3_f32 v0, v0, v50, v51
	v_max3_f32 v0, v0, v52, v53
	v_max3_f32 v0, v0, v54, v55
	v_max3_f32 v0, v0, v56, v57
	v_max3_f32 v0, v0, v58, v59
	v_max3_f32 v0, v0, v60, v61
	v_max3_f32 v0, v0, v62, v63
	v_max3_f32 v0, v0, v32, v33
	v_max3_f32 v0, v0, v34, v35
	v_max3_f32 v0, v0, v36, v37
	v_max3_f32 v0, v0, v38, v39
	v_max3_f32 v0, v0, v40, v41
	v_max3_f32 v0, v0, v42, v43
	v_max3_f32 v0, v0, v44, v45
	v_max3_f32 v0, v0, v46, v47
	v_mov_b32_e32 v1, v0
	s_nop 1
	v_permlane32_swap_b32_e32 v1, v0
	s_and_b64 vcc, exec, s[44:45]
	v_max_f32_e32 v1, v0, v1
	s_cbranch_vccz .LBB0_576
	v_cmp_lt_f32_e32 vcc, s63, v1
	s_mov_b64 s[48:49], 0
	s_mov_b64 s[46:47], 0
	s_cbranch_vccz .LBB0_563
	v_max_f32_e32 v0, v1, v1
	v_max_f32_e32 v0, 0, v0
	s_mov_b64 s[46:47], -1

.LBB0_569:
	v_exp_f32_e32 v0, v48
	v_exp_f32_e32 v148, v49
	v_exp_f32_e32 v2, v50
	v_exp_f32_e32 v150, v51
	v_exp_f32_e32 v4, v52
	v_exp_f32_e32 v152, v53
	v_exp_f32_e32 v6, v54
	v_exp_f32_e32 v154, v55
	v_cvt_pk_bf16_f32 v48, v0, v148
	v_cvt_pk_bf16_f32 v49, v2, v150
	v_cvt_pk_bf16_f32 v50, v4, v152
	v_cvt_pk_bf16_f32 v51, v6, v154
	v_exp_f32_e32 v8, v56
	v_exp_f32_e32 v156, v57
	s_waitcnt lgkmcnt(0)
	v_mfma_f32_32x32x16_bf16 v[96:111], v[12:15], v[48:51], v[96:111]
	v_exp_f32_e32 v10, v58
	v_exp_f32_e32 v158, v59
	v_exp_f32_e32 v12, v60
	v_exp_f32_e32 v160, v61
	v_exp_f32_e32 v14, v62
	v_exp_f32_e32 v162, v63
	v_exp_f32_e32 v1, v32
	v_mfma_f32_32x32x16_bf16 v[80:95], v[144:147], v[48:51], v[80:95]
	v_exp_f32_e32 v149, v33
	v_exp_f32_e32 v3, v34
	v_exp_f32_e32 v151, v35
	v_cvt_pk_bf16_f32 v32, v8, v156
	v_cvt_pk_bf16_f32 v33, v10, v158
	v_cvt_pk_bf16_f32 v34, v12, v160
	v_cvt_pk_bf16_f32 v35, v14, v162
	v_exp_f32_e32 v5, v36
	v_exp_f32_e32 v153, v37
	v_mfma_f32_32x32x16_bf16 v[96:111], v[74:77], v[32:35], v[96:111]
	v_exp_f32_e32 v7, v38
	v_exp_f32_e32 v155, v39
	v_exp_f32_e32 v9, v40
	v_exp_f32_e32 v157, v41
	v_exp_f32_e32 v11, v42
	v_exp_f32_e32 v159, v43
	v_exp_f32_e32 v13, v44
	v_mfma_f32_32x32x16_bf16 v[80:95], v[70:73], v[32:35], v[80:95]
	v_cvt_pk_bf16_f32 v32, v1, v149
	v_cvt_pk_bf16_f32 v33, v3, v151
	v_cvt_pk_bf16_f32 v34, v5, v153
	v_cvt_pk_bf16_f32 v35, v7, v155
	v_exp_f32_e32 v161, v45
	v_exp_f32_e32 v15, v46
	v_exp_f32_e32 v163, v47
	v_mfma_f32_32x32x16_bf16 v[96:111], v[28:31], v[32:35], v[96:111]
	v_add_f32_e64 v28, v0, 0
	v_add_f32_e64 v29, v1, 0
	v_cvt_pk_bf16_f32 v30, v13, v161
	v_add_f32_e64 v28, v148, v28
	v_add_f32_e64 v29, v149, v29
	v_cvt_pk_bf16_f32 v31, v15, v163
	v_pk_add_f32 v[28:29], v[2:3], v[28:29]
	v_mov_b32_e32 v38, v6
	v_pk_add_f32 v[36:37], v[150:151], v[28:29]
	v_mfma_f32_32x32x16_bf16 v[80:95], v[24:27], v[32:35], v[80:95]
	v_add_f32_e64 v24, v4, v36
	v_add_f32_e64 v25, v5, v37
	v_cvt_pk_bf16_f32 v28, v9, v157
	v_add_f32_e64 v24, v152, v24
	v_add_f32_e64 v25, v153, v25
	v_cvt_pk_bf16_f32 v29, v11, v159
	v_pk_add_f32 v[24:25], v[6:7], v[24:25]
	v_mov_b32_e32 v32, v0
	v_pk_add_f32 v[24:25], v[154:155], v[24:25]
	v_mfma_f32_32x32x16_bf16 v[96:111], v[20:23], v[28:31], v[96:111]
	v_add_f32_e64 v24, v8, v24
	v_add_f32_e64 v25, v9, v25
	v_mov_b32_e32 v33, v148
	v_add_f32_e64 v24, v156, v24
	v_add_f32_e64 v25, v157, v25
	v_mov_b32_e32 v34, v2
	v_pk_add_f32 v[20:21], v[10:11], v[24:25]
	v_mov_b32_e32 v35, v150
	v_pk_add_f32 v[20:21], v[158:159], v[20:21]
	v_mfma_f32_32x32x16_bf16 v[80:95], v[16:19], v[28:31], v[80:95]
	v_add_f32_e64 v20, v12, v20
	v_add_f32_e64 v21, v13, v21
	v_mov_b32_e32 v36, v4
	v_add_f32_e64 v20, v160, v20
	v_add_f32_e64 v21, v161, v21
	v_mov_b32_e32 v37, v152
	v_pk_add_f32 v[20:21], v[14:15], v[20:21]
	v_mov_b32_e32 v39, v154
	v_pk_add_f32 v[20:21], v[162:163], v[20:21]
	v_mov_b32_e32 v40, v8
	v_add_f32_e32 v20, v20, v21
	v_add_f32_e32 v171, v171, v20
	v_mov_b32_e32 v41, v156
	v_mov_b32_e32 v42, v10
	v_mov_b32_e32 v43, v158
	v_mov_b32_e32 v44, v12
	v_mov_b32_e32 v45, v160
	v_mov_b32_e32 v46, v14
	v_mov_b32_e32 v47, v162
	v_mov_b32_e32 v48, v1
	v_mov_b32_e32 v49, v149
	v_mov_b32_e32 v50, v3
	v_mov_b32_e32 v51, v151
	v_mov_b32_e32 v52, v5
	v_mov_b32_e32 v53, v153
	v_mov_b32_e32 v54, v7
	v_mov_b32_e32 v55, v155
	v_mov_b32_e32 v56, v9
	v_mov_b32_e32 v57, v157
	v_mov_b32_e32 v58, v11
	v_mov_b32_e32 v59, v159
	v_mov_b32_e32 v60, v13
	v_mov_b32_e32 v61, v161
	v_mov_b32_e32 v62, v15
	v_mov_b32_e32 v63, v163
	s_mov_b64 s[44:45], 0
	v_mov_b32_e32 v31, v163
	v_mov_b32_e32 v30, v15
	v_mov_b32_e32 v29, v161
	v_mov_b32_e32 v28, v13
	v_mov_b32_e32 v27, v159
	v_mov_b32_e32 v26, v11
	v_mov_b32_e32 v25, v157
	v_mov_b32_e32 v24, v9
	v_mov_b32_e32 v23, v155
	v_mov_b32_e32 v22, v7
	v_mov_b32_e32 v21, v153
	v_mov_b32_e32 v20, v5
	v_mov_b32_e32 v19, v151
	v_mov_b32_e32 v18, v3
	v_mov_b32_e32 v17, v149
	v_mov_b32_e32 v16, v1
	v_mov_b32_e32 v15, v162
	v_mov_b32_e32 v13, v160
	v_mov_b32_e32 v11, v158
	v_mov_b32_e32 v9, v156
	v_mov_b32_e32 v7, v154
	v_mov_b32_e32 v5, v152
	v_mov_b32_e32 v3, v150
	v_mov_b32_e32 v1, v148
	s_andn2_b64 vcc, exec, s[42:43]
	s_cbranch_vccz .LBB0_571
	s_branch .LBB0_574

.LBB0_586:
	s_waitcnt lgkmcnt(6)
	v_mfma_f32_32x32x16_bf16 v[0:15], v[66:69], v[136:139], v[0:15]
	ds_read_b128 v[60:63], v64 offset:9216
	ds_read_b128 v[52:55], v64 offset:9248
	ds_read_b128 v[44:47], v64 offset:9280
	ds_read_b128 v[36:39], v64 offset:9312
	ds_read_b128 v[56:59], v64 offset:13824
	ds_read_b128 v[48:51], v64 offset:13856
	ds_read_b128 v[40:43], v64 offset:13888
	ds_read_b128 v[32:35], v64 offset:13920
	s_xor_b64 s[2:3], s[44:45], -1
	s_waitcnt lgkmcnt(10)
	v_mfma_f32_32x32x16_bf16 v[112:127], v[70:73], v[136:139], v[112:127]
	v_mfma_f32_32x32x16_bf16 v[0:15], v[24:27], v[132:135], v[0:15]
	s_waitcnt lgkmcnt(9)
	v_mfma_f32_32x32x16_bf16 v[112:127], v[28:31], v[132:135], v[112:127]
	v_mfma_f32_32x32x16_bf16 v[0:15], v[20:23], v[128:131], v[0:15]
	s_waitcnt lgkmcnt(8)
	v_mfma_f32_32x32x16_bf16 v[112:127], v[16:19], v[128:131], v[112:127]
	s_nop 9
	v_max_f32_e32 v16, v1, v1
	v_max_f32_e32 v17, v0, v0
	v_max_f32_e32 v16, v17, v16
	v_max3_f32 v16, v16, v2, v3
	v_max3_f32 v16, v16, v4, v5
	v_max3_f32 v16, v16, v6, v7
	v_max3_f32 v16, v16, v8, v9
	v_max3_f32 v16, v16, v10, v11
	v_max3_f32 v16, v16, v12, v13
	v_max3_f32 v16, v16, v14, v15
	v_max3_f32 v16, v16, v112, v113
	v_max3_f32 v16, v16, v114, v115
	v_max3_f32 v16, v16, v116, v117
	v_max3_f32 v16, v16, v118, v119
	v_max3_f32 v16, v16, v120, v121
	v_max3_f32 v16, v16, v122, v123
	v_max3_f32 v16, v16, v124, v125
	v_max3_f32 v16, v16, v126, v127
	v_mov_b32_e32 v17, v16
	s_nop 1
	v_permlane32_swap_b32_e32 v17, v16
	s_and_b64 vcc, exec, s[2:3]
	v_max_f32_e32 v16, v16, v17
	s_cbranch_vccz .LBB0_597
	v_cmp_lt_f32_e32 vcc, s63, v16
	s_mov_b64 s[40:41], 0
	s_mov_b64 s[4:5], 0
	s_cbranch_vccz .LBB0_589
	v_max_f32_e32 v17, v16, v16
	v_max_f32_e32 v64, 0, v17
	s_mov_b64 s[4:5], -1

.LBB0_595:
	v_exp_f32_e32 v16, v0
	v_exp_f32_e32 v18, v1
	v_exp_f32_e32 v20, v2
	v_exp_f32_e32 v22, v3
	v_exp_f32_e32 v24, v4
	v_exp_f32_e32 v26, v5
	v_exp_f32_e32 v28, v6
	v_exp_f32_e32 v30, v7
	v_cvt_pk_bf16_f32 v0, v16, v18
	v_cvt_pk_bf16_f32 v1, v20, v22
	v_cvt_pk_bf16_f32 v2, v24, v26
	v_cvt_pk_bf16_f32 v3, v28, v30
	v_exp_f32_e32 v8, v8
	v_exp_f32_e32 v66, v9
	s_waitcnt lgkmcnt(0)
	v_mfma_f32_32x32x16_bf16 v[96:111], v[60:63], v[0:3], v[96:111]
	v_exp_f32_e32 v10, v10
	v_exp_f32_e32 v68, v11
	v_exp_f32_e32 v12, v12
	v_exp_f32_e32 v60, v13
	v_exp_f32_e32 v14, v14
	v_exp_f32_e32 v62, v15
	v_exp_f32_e32 v17, v112
	v_mfma_f32_32x32x16_bf16 v[80:95], v[56:59], v[0:3], v[80:95]
	v_cvt_pk_bf16_f32 v0, v8, v66
	v_cvt_pk_bf16_f32 v1, v10, v68
	v_cvt_pk_bf16_f32 v2, v12, v60
	v_cvt_pk_bf16_f32 v3, v14, v62
	v_exp_f32_e32 v19, v113
	v_exp_f32_e32 v21, v114
	v_exp_f32_e32 v23, v115
	v_mfma_f32_32x32x16_bf16 v[96:111], v[52:55], v[0:3], v[96:111]
	v_exp_f32_e32 v25, v116
	v_exp_f32_e32 v27, v117
	v_exp_f32_e32 v29, v118
	v_exp_f32_e32 v31, v119
	v_pk_add_f32 v[4:5], v[16:17], 0 op_sel_hi:[1,0]
	v_exp_f32_e32 v9, v120
	v_pk_add_f32 v[4:5], v[18:19], v[4:5]
	v_mfma_f32_32x32x16_bf16 v[80:95], v[48:51], v[0:3], v[80:95]
	v_cvt_pk_bf16_f32 v0, v17, v19
	v_cvt_pk_bf16_f32 v1, v21, v23
	v_cvt_pk_bf16_f32 v2, v25, v27
	v_cvt_pk_bf16_f32 v3, v29, v31
	v_add_f32_e64 v4, v20, v4
	v_add_f32_e64 v5, v21, v5
	v_exp_f32_e32 v67, v121
	v_pk_add_f32 v[16:17], v[22:23], v[4:5]
	v_mfma_f32_32x32x16_bf16 v[96:111], v[44:47], v[0:3], v[96:111]
	v_exp_f32_e32 v11, v122
	v_exp_f32_e32 v69, v123
	v_exp_f32_e32 v13, v124
	v_exp_f32_e32 v61, v125
	v_exp_f32_e32 v15, v126
	v_exp_f32_e32 v63, v127
	v_cvt_pk_bf16_f32 v4, v9, v67
	v_mfma_f32_32x32x16_bf16 v[80:95], v[40:43], v[0:3], v[80:95]
	v_add_f32_e64 v0, v24, v16
	v_add_f32_e64 v1, v25, v17
	v_cvt_pk_bf16_f32 v5, v11, v69
	v_add_f32_e64 v0, v26, v0
	v_add_f32_e64 v1, v27, v1
	v_cvt_pk_bf16_f32 v6, v13, v61
	v_pk_add_f32 v[0:1], v[28:29], v[0:1]
	v_cvt_pk_bf16_f32 v7, v15, v63
	v_pk_add_f32 v[0:1], v[30:31], v[0:1]
	s_nop 0
	v_pk_add_f32 v[0:1], v[8:9], v[0:1]
	v_mfma_f32_32x32x16_bf16 v[96:111], v[36:39], v[4:7], v[96:111]
	v_add_f32_e64 v0, v66, v0
	v_add_f32_e64 v1, v67, v1
	v_add_f32_e64 v0, v10, v0
	v_add_f32_e64 v1, v11, v1
	v_add_f32_e64 v0, v68, v0
	v_add_f32_e64 v1, v69, v1
	v_pk_add_f32 v[0:1], v[12:13], v[0:1]
	v_mfma_f32_32x32x16_bf16 v[80:95], v[32:35], v[4:7], v[80:95]
	v_add_f32_e64 v0, v60, v0
	v_add_f32_e64 v1, v61, v1
	v_add_f32_e64 v0, v14, v0
	v_add_f32_e64 v1, v15, v1
	v_add_f32_e64 v0, v62, v0
	v_add_f32_e64 v1, v63, v1
	v_add_f32_e32 v0, v0, v1
	v_add_f32_e32 v171, v171, v0

.LBB0_1341:
	s_cmp_gt_i32 s54, s51
	s_cselect_b64 s[48:49], -1, 0
	s_or_b64 s[48:49], s[44:45], s[48:49]
	s_and_b64 vcc, exec, s[48:49]
	s_cbranch_vccnz .LBB0_1350
	s_xor_b64 s[48:49], s[4:5], -1
	s_bitcmp1_b32 s54, 0
	s_cselect_b32 s4, 0x5c00, 0
	s_add_i32 s4, s4, 0
	v_add3_u32 v160, s4, v173, v144
	ds_read_b128 v[48:51], v160
	ds_read_b128 v[112:115], v160 offset:32
	ds_read_b128 v[116:119], v160 offset:64
	ds_read_b128 v[120:123], v160 offset:96
	ds_read_b128 v[124:127], v160 offset:4608
	ds_read_b128 v[128:131], v160 offset:4640
	ds_read_b128 v[132:135], v160 offset:4672
	ds_read_b128 v[136:139], v160 offset:4704
	s_waitcnt lgkmcnt(7)
	v_mfma_f32_32x32x16_bf16 v[64:79], v[48:51], v[100:103], v[0:15]
	s_waitcnt lgkmcnt(3)
	v_mfma_f32_32x32x16_bf16 v[48:63], v[124:127], v[100:103], v[0:15]
	v_mfma_f32_32x32x16_bf16 v[64:79], v[112:115], v[96:99], v[64:79]
	s_waitcnt lgkmcnt(2)
	v_mfma_f32_32x32x16_bf16 v[48:63], v[128:131], v[96:99], v[48:63]
	v_mfma_f32_32x32x16_bf16 v[64:79], v[116:119], v[92:95], v[64:79]
	s_waitcnt lgkmcnt(1)
	v_mfma_f32_32x32x16_bf16 v[48:63], v[132:135], v[92:95], v[48:63]
	v_mfma_f32_32x32x16_bf16 v[64:79], v[120:123], v[88:91], v[64:79]
	v_add3_u32 v120, s4, v171, v144
	ds_read_b128 v[112:115], v120 offset:18432
	ds_read_b128 v[116:119], v120 offset:18464
	s_waitcnt lgkmcnt(2)
	v_mfma_f32_32x32x16_bf16 v[48:63], v[136:139], v[88:91], v[48:63]
	s_waitcnt lgkmcnt(1)
	v_mfma_f32_32x32x16_bf16 v[64:79], v[112:115], v[84:87], v[64:79]
	ds_read_b128 v[112:115], v120 offset:20992
	ds_read_b128 v[174:177], v120 offset:21024
	s_waitcnt lgkmcnt(1)
	v_mfma_f32_32x32x16_bf16 v[48:63], v[112:115], v[84:87], v[48:63]
	v_mfma_f32_32x32x16_bf16 v[64:79], v[116:119], v[80:83], v[64:79]
	ds_read_b128 v[140:143], v160 offset:9216
	ds_read_b128 v[132:135], v160 offset:9248
	ds_read_b128 v[124:127], v160 offset:9280
	ds_read_b128 v[116:119], v160 offset:9312
	ds_read_b128 v[136:139], v160 offset:13824
	ds_read_b128 v[128:131], v160 offset:13856
	ds_read_b128 v[120:123], v160 offset:13888
	ds_read_b128 v[112:115], v160 offset:13920
	s_waitcnt lgkmcnt(8)
	v_mfma_f32_32x32x16_bf16 v[48:63], v[174:177], v[80:83], v[48:63]
	s_nop 1
	v_max_f32_e32 v160, v65, v65
	v_max_f32_e32 v174, v64, v64
	v_max_f32_e32 v160, v174, v160
	v_max3_f32 v160, v160, v66, v67
	v_max3_f32 v160, v160, v68, v69
	v_max3_f32 v160, v160, v70, v71
	v_max3_f32 v160, v160, v72, v73
	v_max3_f32 v160, v160, v74, v75
	v_max3_f32 v160, v160, v76, v77
	v_max3_f32 v160, v160, v78, v79
	v_max3_f32 v160, v160, v48, v49
	v_max3_f32 v160, v160, v50, v51
	v_max3_f32 v160, v160, v52, v53
	v_max3_f32 v160, v160, v54, v55
	v_max3_f32 v160, v160, v56, v57
	v_max3_f32 v160, v160, v58, v59
	v_max3_f32 v160, v160, v60, v61
	v_max3_f32 v160, v160, v62, v63
	v_mov_b32_e32 v174, v160
	s_nop 1
	v_permlane32_swap_b32_e32 v174, v160
	s_andn2_b64 vcc, exec, s[48:49]
	v_max_f32_e32 v160, v160, v174
	v_cndmask_b32_e64 v174, 0, 1, s[48:49]
	v_cmp_ne_u32_e64 s[4:5], 1, v174
	s_mov_b64 s[48:49], -1
	s_cbranch_vccnz .LBB0_1345
	v_cmp_lt_f32_e32 vcc, s72, v160
	s_cbranch_vccz .LBB0_1358
	v_max_f32_e32 v160, v160, v160
	v_max_f32_e32 v160, 0, v160

.LBB0_1349:
	v_exp_f32_e32 v174, v64
	v_exp_f32_e32 v176, v65
	v_exp_f32_e32 v182, v66
	v_exp_f32_e32 v184, v67
	v_exp_f32_e32 v68, v68
	v_exp_f32_e32 v186, v69
	v_exp_f32_e32 v70, v70
	v_exp_f32_e32 v188, v71
	v_cvt_pk_bf16_f32 v64, v174, v176
	v_cvt_pk_bf16_f32 v65, v182, v184
	v_cvt_pk_bf16_f32 v66, v68, v186
	v_cvt_pk_bf16_f32 v67, v70, v188
	v_exp_f32_e32 v72, v72
	v_exp_f32_e32 v190, v73
	s_waitcnt lgkmcnt(0)
	v_mfma_f32_32x32x16_bf16 v[32:47], v[140:143], v[64:67], v[32:47]
	v_exp_f32_e32 v74, v74
	v_exp_f32_e32 v192, v75
	v_exp_f32_e32 v76, v76
	v_exp_f32_e32 v140, v77
	v_exp_f32_e32 v78, v78
	v_exp_f32_e32 v142, v79
	v_exp_f32_e32 v175, v48
	v_mfma_f32_32x32x16_bf16 v[16:31], v[136:139], v[64:67], v[16:31]
	v_exp_f32_e32 v177, v49
	v_exp_f32_e32 v183, v50
	v_exp_f32_e32 v185, v51
	v_cvt_pk_bf16_f32 v48, v72, v190
	v_cvt_pk_bf16_f32 v49, v74, v192
	v_cvt_pk_bf16_f32 v50, v76, v140
	v_cvt_pk_bf16_f32 v51, v78, v142
	v_exp_f32_e32 v69, v52
	v_exp_f32_e32 v187, v53
	v_mfma_f32_32x32x16_bf16 v[32:47], v[132:135], v[48:51], v[32:47]
	v_exp_f32_e32 v71, v54
	v_exp_f32_e32 v189, v55
	v_pk_add_f32 v[52:53], v[174:175], 0 op_sel_hi:[1,0]
	v_exp_f32_e32 v73, v56
	v_pk_add_f32 v[52:53], v[176:177], v[52:53]
	v_exp_f32_e32 v191, v57
	v_pk_add_f32 v[52:53], v[182:183], v[52:53]
	v_mfma_f32_32x32x16_bf16 v[16:31], v[128:131], v[48:51], v[16:31]
	v_cvt_pk_bf16_f32 v48, v175, v177
	v_cvt_pk_bf16_f32 v49, v183, v185
	v_cvt_pk_bf16_f32 v50, v69, v187
	v_cvt_pk_bf16_f32 v51, v71, v189
	v_add_f32_e64 v56, v184, v52
	v_add_f32_e64 v57, v185, v53
	v_exp_f32_e32 v75, v58
	v_exp_f32_e32 v193, v59
	v_mfma_f32_32x32x16_bf16 v[32:47], v[124:127], v[48:51], v[32:47]
	v_exp_f32_e32 v77, v60
	v_exp_f32_e32 v141, v61
	v_exp_f32_e32 v79, v62
	v_exp_f32_e32 v143, v63
	v_cvt_pk_bf16_f32 v52, v73, v191
	v_cvt_pk_bf16_f32 v53, v75, v193
	v_cvt_pk_bf16_f32 v54, v77, v141
	v_mfma_f32_32x32x16_bf16 v[16:31], v[120:123], v[48:51], v[16:31]
	v_add_f32_e64 v48, v68, v56
	v_add_f32_e64 v49, v69, v57
	v_cvt_pk_bf16_f32 v55, v79, v143
	v_add_f32_e64 v48, v186, v48
	v_add_f32_e64 v49, v187, v49
	s_mov_b64 s[4:5], 0
	v_pk_add_f32 v[48:49], v[70:71], v[48:49]
	s_nop 0
	v_pk_add_f32 v[48:49], v[188:189], v[48:49]
	v_mfma_f32_32x32x16_bf16 v[32:47], v[116:119], v[52:55], v[32:47]
	v_add_f32_e64 v48, v72, v48
	v_add_f32_e64 v49, v73, v49
	v_add_f32_e64 v48, v190, v48
	v_add_f32_e64 v49, v191, v49
	v_add_f32_e64 v48, v74, v48
	v_add_f32_e64 v49, v75, v49
	v_pk_add_f32 v[48:49], v[192:193], v[48:49]
	v_mfma_f32_32x32x16_bf16 v[16:31], v[112:115], v[52:55], v[16:31]
	v_add_f32_e64 v48, v76, v48
	v_add_f32_e64 v49, v77, v49
	v_add_f32_e64 v48, v140, v48
	v_add_f32_e64 v49, v141, v49
	v_add_f32_e64 v48, v78, v48
	v_add_f32_e64 v49, v79, v49
	v_pk_add_f32 v[48:49], v[142:143], v[48:49]
	s_nop 0
	v_add_f32_e32 v48, v48, v49
	v_add_f32_e32 v164, v164, v48

.LBB0_1359:
	s_cmp_gt_i32 s52, s51
	s_cselect_b64 s[2:3], -1, 0
	s_or_b64 s[2:3], s[44:45], s[2:3]
	s_and_b64 vcc, exec, s[2:3]
	s_cbranch_vccnz .LBB0_1368
	s_xor_b64 s[4:5], s[4:5], -1
	s_bitcmp1_b32 s52, 0
	s_cselect_b32 s2, 0x5c00, 0
	s_add_i32 s2, s2, 0
	v_add3_u32 v120, s2, v173, v144
	ds_read_b128 v[64:67], v120
	ds_read_b128 v[68:71], v120 offset:32
	ds_read_b128 v[72:75], v120 offset:64
	ds_read_b128 v[76:79], v120 offset:96
	s_waitcnt vmcnt(0)
	ds_read_b128 v[104:107], v120 offset:4608
	ds_read_b128 v[108:111], v120 offset:4640
	ds_read_b128 v[112:115], v120 offset:4672
	ds_read_b128 v[116:119], v120 offset:4704
	s_waitcnt lgkmcnt(7)
	v_mfma_f32_32x32x16_bf16 v[48:63], v[64:67], v[100:103], v[0:15]
	s_waitcnt lgkmcnt(3)
	v_mfma_f32_32x32x16_bf16 v[0:15], v[104:107], v[100:103], v[0:15]
	v_mfma_f32_32x32x16_bf16 v[48:63], v[68:71], v[96:99], v[48:63]
	s_waitcnt lgkmcnt(2)
	v_mfma_f32_32x32x16_bf16 v[0:15], v[108:111], v[96:99], v[0:15]
	v_mfma_f32_32x32x16_bf16 v[48:63], v[72:75], v[92:95], v[48:63]
	v_add3_u32 v72, s2, v171, v144
	ds_read_b128 v[64:67], v72 offset:18432
	ds_read_b128 v[68:71], v72 offset:18464
	s_waitcnt lgkmcnt(3)
	v_mfma_f32_32x32x16_bf16 v[0:15], v[112:115], v[92:95], v[0:15]
	v_mfma_f32_32x32x16_bf16 v[48:63], v[76:79], v[88:91], v[48:63]
	s_waitcnt lgkmcnt(2)
	v_mfma_f32_32x32x16_bf16 v[0:15], v[116:119], v[88:91], v[0:15]
	s_waitcnt lgkmcnt(1)
	v_mfma_f32_32x32x16_bf16 v[48:63], v[64:67], v[84:87], v[48:63]
	ds_read_b128 v[64:67], v72 offset:20992
	ds_read_b128 v[72:75], v72 offset:21024
	s_waitcnt lgkmcnt(1)
	v_mfma_f32_32x32x16_bf16 v[0:15], v[64:67], v[84:87], v[0:15]
	ds_read_b128 v[112:115], v120 offset:9216
	ds_read_b128 v[104:107], v120 offset:9248
	ds_read_b128 v[96:99], v120 offset:9280
	ds_read_b128 v[88:91], v120 offset:9312
	ds_read_b128 v[108:111], v120 offset:13824
	ds_read_b128 v[100:103], v120 offset:13856
	ds_read_b128 v[92:95], v120 offset:13888
	ds_read_b128 v[84:87], v120 offset:13920
	v_mfma_f32_32x32x16_bf16 v[48:63], v[68:71], v[80:83], v[48:63]
	s_waitcnt lgkmcnt(8)
	v_mfma_f32_32x32x16_bf16 v[0:15], v[72:75], v[80:83], v[0:15]
	s_nop 9
	v_max_f32_e32 v64, v49, v49
	v_max_f32_e32 v65, v48, v48
	v_max_f32_e32 v64, v65, v64
	v_max3_f32 v64, v64, v50, v51
	v_max3_f32 v64, v64, v52, v53
	v_max3_f32 v64, v64, v54, v55
	v_max3_f32 v64, v64, v56, v57
	v_max3_f32 v64, v64, v58, v59
	v_max3_f32 v64, v64, v60, v61
	v_max3_f32 v64, v64, v62, v63
	v_max3_f32 v64, v64, v0, v1
	v_max3_f32 v64, v64, v2, v3
	v_max3_f32 v64, v64, v4, v5
	v_max3_f32 v64, v64, v6, v7
	v_max3_f32 v64, v64, v8, v9
	v_max3_f32 v64, v64, v10, v11
	v_max3_f32 v64, v64, v12, v13
	v_max3_f32 v64, v64, v14, v15
	v_mov_b32_e32 v65, v64
	s_nop 1
	v_permlane32_swap_b32_e32 v65, v64
	s_andn2_b64 vcc, exec, s[4:5]
	v_max_f32_e32 v80, v64, v65
	v_cndmask_b32_e64 v64, 0, 1, s[4:5]
	v_cmp_ne_u32_e64 s[2:3], 1, v64
	s_mov_b64 s[4:5], -1
	s_cbranch_vccnz .LBB0_1363
	v_cmp_lt_f32_e32 vcc, s72, v80
	s_cbranch_vccz .LBB0_1370
	v_max_f32_e32 v64, v80, v80
	v_max_f32_e32 v80, 0, v64

.LBB0_1367:
	v_exp_f32_e32 v64, v48
	v_exp_f32_e32 v66, v49
	v_exp_f32_e32 v68, v50
	v_exp_f32_e32 v70, v51
	v_exp_f32_e32 v52, v52
	v_exp_f32_e32 v72, v53
	v_exp_f32_e32 v54, v54
	v_exp_f32_e32 v74, v55
	v_cvt_pk_bf16_f32 v48, v64, v66
	v_cvt_pk_bf16_f32 v49, v68, v70
	v_cvt_pk_bf16_f32 v50, v52, v72
	v_cvt_pk_bf16_f32 v51, v54, v74
	v_exp_f32_e32 v56, v56
	v_exp_f32_e32 v76, v57
	s_waitcnt lgkmcnt(0)
	v_mfma_f32_32x32x16_bf16 v[32:47], v[112:115], v[48:51], v[32:47]
	v_exp_f32_e32 v58, v58
	v_exp_f32_e32 v78, v59
	v_exp_f32_e32 v60, v60
	v_exp_f32_e32 v80, v61
	v_exp_f32_e32 v62, v62
	v_exp_f32_e32 v82, v63
	v_exp_f32_e32 v65, v0
	v_mfma_f32_32x32x16_bf16 v[16:31], v[108:111], v[48:51], v[16:31]
	v_exp_f32_e32 v67, v1
	v_exp_f32_e32 v69, v2
	v_exp_f32_e32 v71, v3
	v_cvt_pk_bf16_f32 v0, v56, v76
	v_cvt_pk_bf16_f32 v1, v58, v78
	v_cvt_pk_bf16_f32 v2, v60, v80
	v_cvt_pk_bf16_f32 v3, v62, v82
	v_exp_f32_e32 v53, v4
	v_exp_f32_e32 v73, v5
	v_mfma_f32_32x32x16_bf16 v[32:47], v[104:107], v[0:3], v[32:47]
	v_exp_f32_e32 v55, v6
	v_exp_f32_e32 v75, v7
	v_pk_add_f32 v[4:5], v[64:65], 0 op_sel_hi:[1,0]
	v_exp_f32_e32 v57, v8
	v_pk_add_f32 v[4:5], v[66:67], v[4:5]
	v_exp_f32_e32 v77, v9
	v_pk_add_f32 v[4:5], v[68:69], v[4:5]
	v_mfma_f32_32x32x16_bf16 v[16:31], v[100:103], v[0:3], v[16:31]
	v_cvt_pk_bf16_f32 v0, v65, v67
	v_cvt_pk_bf16_f32 v1, v69, v71
	v_cvt_pk_bf16_f32 v2, v53, v73
	v_cvt_pk_bf16_f32 v3, v55, v75
	v_add_f32_e64 v8, v70, v4
	v_add_f32_e64 v9, v71, v5
	v_exp_f32_e32 v59, v10
	v_exp_f32_e32 v79, v11
	v_mfma_f32_32x32x16_bf16 v[32:47], v[96:99], v[0:3], v[32:47]
	v_exp_f32_e32 v61, v12
	v_exp_f32_e32 v81, v13
	v_exp_f32_e32 v63, v14
	v_exp_f32_e32 v83, v15
	v_cvt_pk_bf16_f32 v4, v57, v77
	v_cvt_pk_bf16_f32 v5, v59, v79
	v_cvt_pk_bf16_f32 v6, v61, v81
	v_mfma_f32_32x32x16_bf16 v[16:31], v[92:95], v[0:3], v[16:31]
	v_add_f32_e64 v0, v52, v8
	v_add_f32_e64 v1, v53, v9
	v_cvt_pk_bf16_f32 v7, v63, v83
	v_add_f32_e64 v0, v72, v0
	v_add_f32_e64 v1, v73, v1
	v_pk_add_f32 v[0:1], v[54:55], v[0:1]
	s_nop 0
	v_pk_add_f32 v[0:1], v[74:75], v[0:1]
	v_mfma_f32_32x32x16_bf16 v[32:47], v[88:91], v[4:7], v[32:47]
	v_add_f32_e64 v0, v56, v0
	v_add_f32_e64 v1, v57, v1
	v_add_f32_e64 v0, v76, v0
	v_add_f32_e64 v1, v77, v1
	v_add_f32_e64 v0, v58, v0
	v_add_f32_e64 v1, v59, v1
	v_pk_add_f32 v[0:1], v[78:79], v[0:1]
	v_mfma_f32_32x32x16_bf16 v[16:31], v[84:87], v[4:7], v[16:31]
	v_add_f32_e64 v0, v60, v0
	v_add_f32_e64 v1, v61, v1
	v_add_f32_e64 v0, v80, v0
	v_add_f32_e64 v1, v81, v1
	v_add_f32_e64 v0, v62, v0
	v_add_f32_e64 v1, v63, v1
	v_pk_add_f32 v[0:1], v[82:83], v[0:1]
	s_nop 0
	v_add_f32_e32 v0, v0, v1
	v_add_f32_e32 v164, v164, v0

.LBB0_1512:
	s_cmp_lt_i32 s20, 11
	s_cselect_b64 s[4:5], -1, 0
	s_and_b64 s[2:3], s[4:5], s[2:3]
	s_andn2_b64 vcc, exec, s[2:3]
	s_cbranch_vccnz .LBB0_1572
	s_mov_b64 s[70:71], 0x10000
	s_mov_b64 s[72:73], 0x30000
	s_mov_b64 s[74:75], 0x8000
	s_cmpk_lt_i32 s12, 0x404
	s_movk_i32 s2, 0x400
	s_cselect_b64 s[4:5], -1, 0
	s_cmpk_gt_i32 s12, 0x403
	s_nop 0
	v_readfirstlane_b32 s24, v181
	s_cbranch_scc1 .LBB0_1515
	s_ashr_i32 s3, s12, 31
	s_lshr_b32 s3, s3, 29
	s_add_i32 s3, s12, s3
	s_ashr_i32 s6, s3, 3
	s_and_b32 s3, s3, -8
	s_sub_i32 s3, s12, s3
	s_lshl_b32 s8, s3, 7
	s_or_b32 s8, s8, 4
	s_mul_i32 s7, s3, 0x81
	s_cmp_lt_i32 s3, 4
	s_cselect_b32 s3, s7, s8
	s_add_i32 s3, s3, s6
	s_ashr_i32 s6, s3, 31
	s_lshr_b32 s6, s6, 27
	s_add_i32 s6, s3, s6
	s_ashr_i32 s7, s6, 5
	s_lshl_b32 s8, s7, 3
	s_sub_i32 s7, 0x101, s8
	s_min_u32 s9, s7, 8
	s_andn2_b32 s6, s6, 31
	s_sub_i32 s3, s3, s6
	v_cvt_f32_ubyte0_e32 v1, s9
	v_cvt_f32_i32_e32 v0, s3
	v_rcp_iflag_f32_e32 v2, v1
	s_ashr_i32 s6, s3, 30
	s_or_b32 s10, s6, 1
	v_mul_f32_e32 v2, v0, v2
	v_trunc_f32_e32 v2, v2
	v_fma_f32 v0, -v2, v1, v0
	v_cvt_i32_f32_e32 v2, v2
	v_cmp_ge_f32_e64 s[6:7], |v0|, v1
	s_and_b64 s[6:7], s[6:7], exec
	s_cselect_b32 s6, s10, 0
	v_readfirstlane_b32 s7, v2
	s_add_i32 s6, s7, s6
	s_sext_i32_i8 s57, s6
	s_mul_i32 s6, s6, s9
	s_sub_i32 s3, s3, s6
	s_sext_i32_i8 s3, s3
	s_add_i32 s58, s8, s3

.LBB0_1536:
	s_lshl_b32 s30, s58, 8
	s_add_i32 s30, s30, s48
	v_or_b32_e32 v154, s30, v158
	v_cmp_lt_i32_e32 vcc, s53, v154
	s_and_saveexec_b64 s[28:29], vcc
	s_xor_b64 s[28:29], exec, s[28:29]
	v_add_u32_e32 v150, 0xffff0000, v154
	v_mov_b32_e32 v151, v137
	v_lshlrev_b64 v[152:153], 12, v[150:151]
	v_lshrrev_b32_e32 v150, 5, v150
	v_lshl_add_u64 v[156:157], s[16:17], 0, v[152:153]
	v_add_u32_e32 v150, 32, v150
	v_mov_b32_e32 v155, v137
	s_or_saveexec_b64 s[28:29], s[28:29]
	s_ashr_i32 s31, s30, 11
	s_xor_b64 exec, exec, s[28:29]
	v_ashrrev_i32_e32 v155, 31, v154
	v_lshlrev_b64 v[150:151], 12, v[154:155]
	v_lshl_add_u64 v[156:157], s[4:5], 0, v[150:151]
	v_mov_b32_e32 v150, s31
	s_or_b64 exec, exec, s[28:29]
	v_lshl_or_b32 v152, s57, 8, v160
	v_lshlrev_b64 v[166:167], 11, v[154:155]
	v_ashrrev_i32_e32 v153, 31, v152
	v_lshl_add_u64 v[166:167], s[6:7], 0, v[166:167]
	v_lshl_add_u64 v[178:179], v[152:153], 1, v[166:167]
	v_mov_b64_e32 v[170:171], s[18:19]
	global_load_dwordx4 v[198:201], v[178:179], off
	global_load_dwordx4 v[202:205], v[178:179], off offset:64
	v_mad_i64_i32 v[170:171], s[28:29], v150, s54, v[170:171]
	v_lshlrev_b64 v[150:151], 2, v[152:153]
	v_lshl_add_u64 v[180:181], v[170:171], 0, v[150:151]
	global_load_dwordx4 v[224:227], v[180:181], off
	global_load_dwordx4 v[228:231], v[180:181], off offset:16
	global_load_dwordx4 v[232:235], v[180:181], off offset:128
	global_load_dwordx4 v[236:239], v[180:181], off offset:144
	v_lshl_add_u64 v[222:223], v[178:179], 0, s[74:75]
	global_load_dwordx4 v[206:209], v[222:223], off
	global_load_dwordx4 v[210:213], v[222:223], off offset:64
	v_lshl_add_u64 v[222:223], v[178:179], 0, s[70:71]
	global_load_dwordx4 v[214:217], v[222:223], off
	global_load_dwordx4 v[218:221], v[222:223], off offset:64
	v_lshl_add_u64 v[156:157], v[138:139], 2, v[156:157]
	v_lshl_add_u64 v[156:157], v[140:141], 2, v[156:157]
	v_lshl_add_u64 v[156:157], v[156:157], 0, v[136:137]
	v_lshl_add_u64 v[156:157], v[156:157], 0, v[150:151]
	s_waitcnt vmcnt(6)
	v_lshlrev_b32_e32 v182, 16, v198
	v_and_b32_e32 v183, 0xffff0000, v198
	v_lshlrev_b32_e32 v166, 16, v199
	v_and_b32_e32 v167, 0xffff0000, v199
	v_lshlrev_b32_e32 v184, 16, v200
	v_and_b32_e32 v185, 0xffff0000, v200
	v_lshlrev_b32_e32 v168, 16, v201
	v_and_b32_e32 v169, 0xffff0000, v201
	v_pk_fma_f32 v[122:123], v[122:123], v[226:227], v[166:167]
	v_pk_fma_f32 v[120:121], v[120:121], v[224:225], v[182:183]
	v_pk_fma_f32 v[126:127], v[126:127], v[230:231], v[168:169]
	v_pk_fma_f32 v[124:125], v[124:125], v[228:229], v[184:185]
	ds_write_b128 v164, v[120:123]
	ds_write_b128 v164, v[124:127] offset:16
	s_waitcnt lgkmcnt(0)
	ds_read_b128 v[120:123], v165
	ds_read_b128 v[124:127], v165 offset:1152
	v_add_co_u32_e32 v170, vcc, s49, v156
	s_nop 1
	v_addc_co_u32_e32 v171, vcc, 0, v157, vcc
	s_waitcnt lgkmcnt(0)
	global_store_dwordx4 v[156:157], v[120:123], off nt
	global_store_dwordx4 v[170:171], v[124:127], off nt
	s_waitcnt lgkmcnt(0)
	s_waitcnt vmcnt(10)
	v_lshlrev_b32_e32 v172, 16, v202
	v_and_b32_e32 v173, 0xffff0000, v202
	v_lshlrev_b32_e32 v120, 16, v203
	v_and_b32_e32 v121, 0xffff0000, v203
	v_lshlrev_b32_e32 v174, 16, v204
	v_and_b32_e32 v175, 0xffff0000, v204
	v_lshlrev_b32_e32 v122, 16, v205
	v_and_b32_e32 v123, 0xffff0000, v205
	s_waitcnt vmcnt(7)
	v_pk_fma_f32 v[118:119], v[118:119], v[234:235], v[120:121]
	v_pk_fma_f32 v[116:117], v[116:117], v[232:233], v[172:173]
	s_waitcnt vmcnt(6)
	v_pk_fma_f32 v[114:115], v[114:115], v[238:239], v[122:123]
	v_pk_fma_f32 v[112:113], v[112:113], v[236:237], v[174:175]
	ds_write_b128 v164, v[116:119]
	ds_write_b128 v164, v[112:115] offset:16
	s_waitcnt lgkmcnt(0)
	ds_read_b128 v[112:115], v165
	ds_read_b128 v[116:119], v165 offset:1152
	s_waitcnt lgkmcnt(1)
	global_store_dwordx4 v[156:157], v[112:115], off offset:128 nt
	s_waitcnt lgkmcnt(0)
	global_store_dwordx4 v[170:171], v[116:119], off offset:128 nt
	s_waitcnt lgkmcnt(0)
	v_or_b32_e32 v114, 16, v154
	v_cmp_lt_i32_e32 vcc, s53, v114
	s_and_saveexec_b64 s[28:29], vcc
	s_xor_b64 s[28:29], exec, s[28:29]
	v_add_u32_e32 v116, 0xffff0010, v154
	v_mov_b32_e32 v117, v137
	v_lshlrev_b64 v[112:113], 12, v[116:117]
	v_lshrrev_b32_e32 v115, 5, v116
	v_lshl_add_u64 v[112:113], s[16:17], 0, v[112:113]
	v_add_u32_e32 v116, 32, v115
	v_mov_b32_e32 v115, v137
	s_andn2_saveexec_b64 s[28:29], s[28:29]
	v_ashrrev_i32_e32 v115, 31, v114
	v_lshlrev_b64 v[112:113], 12, v[114:115]
	v_lshl_add_u64 v[112:113], s[4:5], 0, v[112:113]
	v_mov_b32_e32 v116, s31
	s_or_b64 exec, exec, s[28:29]
	v_lshlrev_b64 v[114:115], 11, v[114:115]
	v_lshl_add_u64 v[114:115], s[6:7], 0, v[114:115]
	v_lshl_add_u64 v[126:127], v[152:153], 1, v[114:115]
	v_mov_b64_e32 v[114:115], s[18:19]
	v_mad_i64_i32 v[114:115], s[28:29], v116, s54, v[114:115]
	v_lshl_add_u64 v[156:157], v[114:115], 0, v[150:151]
	s_cmpk_lg_i32 s58, 0x100
	s_cbranch_scc1 .Lp10_ng1
	global_load_dwordx4 v[224:227], v[156:157], off
	global_load_dwordx4 v[228:231], v[156:157], off offset:16
	global_load_dwordx4 v[232:235], v[156:157], off offset:128
	global_load_dwordx4 v[236:239], v[156:157], off offset:144
	s_waitcnt vmcnt(0)
.Lp10_ng1:
	v_lshl_add_u64 v[222:223], v[126:127], 0, s[70:71]
	global_load_dwordx4 v[198:201], v[222:223], off
	global_load_dwordx4 v[202:205], v[222:223], off offset:64
	v_lshl_add_u64 v[112:113], v[138:139], 2, v[112:113]
	v_lshl_add_u64 v[112:113], v[140:141], 2, v[112:113]
	v_lshl_add_u64 v[112:113], v[112:113], 0, v[136:137]
	v_lshl_add_u64 v[166:167], v[112:113], 0, v[150:151]
	s_waitcnt vmcnt(9)
	v_lshlrev_b32_e32 v112, 16, v206
	v_and_b32_e32 v113, 0xffff0000, v206
	v_lshlrev_b32_e32 v118, 16, v207
	v_and_b32_e32 v119, 0xffff0000, v207
	v_lshlrev_b32_e32 v168, 16, v208
	v_and_b32_e32 v169, 0xffff0000, v208
	v_lshlrev_b32_e32 v120, 16, v209
	v_and_b32_e32 v121, 0xffff0000, v209
	s_waitcnt vmcnt(13)
	v_pk_fma_f32 v[110:111], v[110:111], v[226:227], v[118:119]
	v_pk_fma_f32 v[108:109], v[108:109], v[224:225], v[112:113]
	s_waitcnt vmcnt(12)
	v_pk_fma_f32 v[106:107], v[106:107], v[230:231], v[120:121]
	v_pk_fma_f32 v[104:105], v[104:105], v[228:229], v[168:169]
	ds_write_b128 v164, v[108:111]
	ds_write_b128 v164, v[104:107] offset:16
	s_waitcnt lgkmcnt(0)
	ds_read_b128 v[104:107], v165
	ds_read_b128 v[108:111], v165 offset:1152
	v_add_co_u32_e32 v116, vcc, s49, v166
	s_nop 1
	v_addc_co_u32_e32 v117, vcc, 0, v167, vcc
	s_waitcnt lgkmcnt(1)
	global_store_dwordx4 v[166:167], v[104:107], off nt
	s_waitcnt lgkmcnt(0)
	global_store_dwordx4 v[116:117], v[108:111], off nt
	s_waitcnt lgkmcnt(0)
	s_waitcnt vmcnt(10)
	v_lshlrev_b32_e32 v118, 16, v210
	v_and_b32_e32 v119, 0xffff0000, v210
	v_lshlrev_b32_e32 v104, 16, v211
	v_and_b32_e32 v105, 0xffff0000, v211
	v_lshlrev_b32_e32 v120, 16, v212
	v_and_b32_e32 v121, 0xffff0000, v212
	v_lshlrev_b32_e32 v106, 16, v213
	v_and_b32_e32 v107, 0xffff0000, v213
	s_waitcnt vmcnt(13)
	v_pk_fma_f32 v[102:103], v[102:103], v[234:235], v[104:105]
	v_pk_fma_f32 v[100:101], v[100:101], v[232:233], v[118:119]
	s_waitcnt vmcnt(12)
	v_pk_fma_f32 v[98:99], v[98:99], v[238:239], v[106:107]
	v_pk_fma_f32 v[96:97], v[96:97], v[236:237], v[120:121]
	ds_write_b128 v164, v[100:103]
	ds_write_b128 v164, v[96:99] offset:16
	s_waitcnt lgkmcnt(0)
	ds_read_b128 v[96:99], v165
	ds_read_b128 v[100:103], v165 offset:1152
	s_waitcnt lgkmcnt(1)
	global_store_dwordx4 v[166:167], v[96:99], off offset:128 nt
	s_waitcnt lgkmcnt(0)
	global_store_dwordx4 v[116:117], v[100:103], off offset:128 nt
	s_waitcnt lgkmcnt(0)
	v_or_b32_e32 v98, 32, v154
	v_cmp_lt_i32_e32 vcc, s53, v98
	s_and_saveexec_b64 s[28:29], vcc
	s_xor_b64 s[28:29], exec, s[28:29]
	v_add_u32_e32 v100, 0xffff0020, v154
	v_mov_b32_e32 v101, v137
	v_lshlrev_b64 v[96:97], 12, v[100:101]
	v_lshrrev_b32_e32 v99, 5, v100
	v_lshl_add_u64 v[96:97], s[16:17], 0, v[96:97]
	v_add_u32_e32 v100, 32, v99
	v_mov_b32_e32 v99, v137
	s_andn2_saveexec_b64 s[28:29], s[28:29]
	v_ashrrev_i32_e32 v99, 31, v98
	v_lshlrev_b64 v[96:97], 12, v[98:99]
	v_lshl_add_u64 v[96:97], s[4:5], 0, v[96:97]
	v_mov_b32_e32 v100, s31
	s_or_b64 exec, exec, s[28:29]
	v_lshlrev_b64 v[98:99], 11, v[98:99]
	v_lshl_add_u64 v[98:99], s[6:7], 0, v[98:99]
	v_lshl_add_u64 v[110:111], v[152:153], 1, v[98:99]
	v_mov_b64_e32 v[98:99], s[18:19]
	v_mad_i64_i32 v[98:99], s[28:29], v100, s54, v[98:99]
	v_lshl_add_u64 v[112:113], v[98:99], 0, v[150:151]
	s_cmpk_lg_i32 s58, 0x100
	s_cbranch_scc1 .Lp10_ng2
	global_load_dwordx4 v[224:227], v[112:113], off
	global_load_dwordx4 v[228:231], v[112:113], off offset:16
	global_load_dwordx4 v[232:235], v[112:113], off offset:128
	global_load_dwordx4 v[236:239], v[112:113], off offset:144
	s_waitcnt vmcnt(0)
.Lp10_ng2:
	v_lshl_add_u64 v[222:223], v[110:111], 0, s[72:73]
	global_load_dwordx4 v[206:209], v[222:223], off
	global_load_dwordx4 v[210:213], v[222:223], off offset:64
	v_lshl_add_u64 v[96:97], v[138:139], 2, v[96:97]
	v_lshl_add_u64 v[96:97], v[140:141], 2, v[96:97]
	v_lshl_add_u64 v[96:97], v[96:97], 0, v[136:137]
	v_lshl_add_u64 v[114:115], v[96:97], 0, v[150:151]
	s_waitcnt vmcnt(13)
	v_lshlrev_b32_e32 v96, 16, v214
	v_and_b32_e32 v97, 0xffff0000, v214
	v_lshlrev_b32_e32 v102, 16, v215
	v_and_b32_e32 v103, 0xffff0000, v215
	v_lshlrev_b32_e32 v116, 16, v216
	v_and_b32_e32 v117, 0xffff0000, v216
	v_lshlrev_b32_e32 v104, 16, v217
	v_and_b32_e32 v105, 0xffff0000, v217
	s_waitcnt vmcnt(19)
	v_pk_fma_f32 v[94:95], v[94:95], v[226:227], v[102:103]
	v_pk_fma_f32 v[92:93], v[92:93], v[224:225], v[96:97]
	s_waitcnt vmcnt(18)
	v_pk_fma_f32 v[90:91], v[90:91], v[230:231], v[104:105]
	v_pk_fma_f32 v[88:89], v[88:89], v[228:229], v[116:117]
	ds_write_b128 v164, v[92:95]
	ds_write_b128 v164, v[88:91] offset:16
	s_waitcnt lgkmcnt(0)
	ds_read_b128 v[88:91], v165
	ds_read_b128 v[92:95], v165 offset:1152
	v_add_co_u32_e32 v100, vcc, s49, v114
	s_nop 1
	v_addc_co_u32_e32 v101, vcc, 0, v115, vcc
	s_waitcnt lgkmcnt(1)
	global_store_dwordx4 v[114:115], v[88:91], off nt
	s_waitcnt lgkmcnt(0)
	global_store_dwordx4 v[100:101], v[92:95], off nt
	s_waitcnt lgkmcnt(0)
	s_waitcnt vmcnt(14)
	v_lshlrev_b32_e32 v102, 16, v218
	v_and_b32_e32 v103, 0xffff0000, v218
	v_lshlrev_b32_e32 v88, 16, v219
	v_and_b32_e32 v89, 0xffff0000, v219
	v_lshlrev_b32_e32 v104, 16, v220
	v_and_b32_e32 v105, 0xffff0000, v220
	v_lshlrev_b32_e32 v90, 16, v221
	v_and_b32_e32 v91, 0xffff0000, v221
	s_waitcnt vmcnt(19)
	v_pk_fma_f32 v[86:87], v[86:87], v[234:235], v[88:89]
	v_pk_fma_f32 v[84:85], v[84:85], v[232:233], v[102:103]
	s_waitcnt vmcnt(18)
	v_pk_fma_f32 v[82:83], v[82:83], v[238:239], v[90:91]
	v_pk_fma_f32 v[80:81], v[80:81], v[236:237], v[104:105]
	ds_write_b128 v164, v[84:87]
	ds_write_b128 v164, v[80:83] offset:16
	s_waitcnt lgkmcnt(0)
	ds_read_b128 v[80:83], v165
	ds_read_b128 v[84:87], v165 offset:1152
	s_waitcnt lgkmcnt(1)
	global_store_dwordx4 v[114:115], v[80:83], off offset:128 nt
	s_waitcnt lgkmcnt(0)
	global_store_dwordx4 v[100:101], v[84:87], off offset:128 nt
	s_waitcnt lgkmcnt(0)
	v_or_b32_e32 v82, 48, v154
	v_cmp_lt_i32_e32 vcc, s53, v82
	s_and_saveexec_b64 s[28:29], vcc
	s_xor_b64 s[28:29], exec, s[28:29]
	v_add_u32_e32 v84, 0xffff0030, v154
	v_mov_b32_e32 v85, v137
	v_lshlrev_b64 v[80:81], 12, v[84:85]
	v_lshrrev_b32_e32 v83, 5, v84
	v_lshl_add_u64 v[80:81], s[16:17], 0, v[80:81]
	v_add_u32_e32 v84, 32, v83
	v_mov_b32_e32 v83, v137
	s_andn2_saveexec_b64 s[28:29], s[28:29]
	v_ashrrev_i32_e32 v83, 31, v82
	v_lshlrev_b64 v[80:81], 12, v[82:83]
	v_lshl_add_u64 v[80:81], s[4:5], 0, v[80:81]
	v_mov_b32_e32 v84, s31
	s_or_b64 exec, exec, s[28:29]
	v_lshlrev_b64 v[82:83], 11, v[82:83]
	v_lshl_add_u64 v[82:83], s[6:7], 0, v[82:83]
	v_lshl_add_u64 v[94:95], v[152:153], 1, v[82:83]
	v_mov_b64_e32 v[82:83], s[18:19]
	v_mad_i64_i32 v[82:83], s[28:29], v84, s54, v[82:83]
	v_lshl_add_u64 v[96:97], v[82:83], 0, v[150:151]
	s_cmpk_lg_i32 s58, 0x100
	s_cbranch_scc1 .Lp10_ng3
	global_load_dwordx4 v[224:227], v[96:97], off
	global_load_dwordx4 v[228:231], v[96:97], off offset:16
	global_load_dwordx4 v[232:235], v[96:97], off offset:128
	global_load_dwordx4 v[236:239], v[96:97], off offset:144
	s_waitcnt vmcnt(0)
.Lp10_ng3:
	v_lshl_add_u64 v[222:223], v[94:95], 0, s[72:73]
	global_load_dwordx4 v[214:217], v[222:223], off
	global_load_dwordx4 v[218:221], v[222:223], off offset:64
	v_lshl_add_u64 v[80:81], v[138:139], 2, v[80:81]
	v_lshl_add_u64 v[80:81], v[140:141], 2, v[80:81]
	v_lshl_add_u64 v[80:81], v[80:81], 0, v[136:137]
	v_lshl_add_u64 v[98:99], v[80:81], 0, v[150:151]
	s_addk_i32 s30, 0x80
	s_waitcnt vmcnt(13)
	v_lshlrev_b32_e32 v80, 16, v198
	v_and_b32_e32 v81, 0xffff0000, v198
	v_lshlrev_b32_e32 v86, 16, v199
	v_and_b32_e32 v87, 0xffff0000, v199
	v_lshlrev_b32_e32 v100, 16, v200
	v_and_b32_e32 v101, 0xffff0000, v200
	v_lshlrev_b32_e32 v88, 16, v201
	v_and_b32_e32 v89, 0xffff0000, v201
	s_waitcnt vmcnt(25)
	v_pk_fma_f32 v[78:79], v[78:79], v[226:227], v[86:87]
	v_pk_fma_f32 v[76:77], v[76:77], v[224:225], v[80:81]
	s_waitcnt vmcnt(24)
	v_pk_fma_f32 v[74:75], v[74:75], v[230:231], v[88:89]
	v_pk_fma_f32 v[72:73], v[72:73], v[228:229], v[100:101]
	ds_write_b128 v164, v[76:79]
	ds_write_b128 v164, v[72:75] offset:16
	s_waitcnt lgkmcnt(0)
	ds_read_b128 v[72:75], v165
	ds_read_b128 v[76:79], v165 offset:1152
	v_add_co_u32_e32 v84, vcc, s49, v98
	s_nop 1
	v_addc_co_u32_e32 v85, vcc, 0, v99, vcc
	s_waitcnt lgkmcnt(1)
	global_store_dwordx4 v[98:99], v[72:75], off nt
	s_waitcnt lgkmcnt(0)
	global_store_dwordx4 v[84:85], v[76:79], off nt
	s_waitcnt lgkmcnt(0)
	s_waitcnt vmcnt(14)
	v_lshlrev_b32_e32 v86, 16, v202
	v_and_b32_e32 v87, 0xffff0000, v202
	v_lshlrev_b32_e32 v72, 16, v203
	v_and_b32_e32 v73, 0xffff0000, v203
	v_lshlrev_b32_e32 v88, 16, v204
	v_and_b32_e32 v89, 0xffff0000, v204
	v_lshlrev_b32_e32 v74, 16, v205
	v_and_b32_e32 v75, 0xffff0000, v205
	s_waitcnt vmcnt(25)
	v_pk_fma_f32 v[70:71], v[70:71], v[234:235], v[72:73]
	v_pk_fma_f32 v[68:69], v[68:69], v[232:233], v[86:87]
	s_waitcnt vmcnt(24)
	v_pk_fma_f32 v[66:67], v[66:67], v[238:239], v[74:75]
	v_pk_fma_f32 v[64:65], v[64:65], v[236:237], v[88:89]
	ds_write_b128 v164, v[68:71]
	ds_write_b128 v164, v[64:67] offset:16
	s_waitcnt lgkmcnt(0)
	ds_read_b128 v[64:67], v165
	ds_read_b128 v[68:71], v165 offset:1152
	s_waitcnt lgkmcnt(1)
	global_store_dwordx4 v[98:99], v[64:67], off offset:128 nt
	s_waitcnt lgkmcnt(0)
	global_store_dwordx4 v[84:85], v[68:71], off offset:128 nt
	s_waitcnt lgkmcnt(0)
	v_or_b32_e32 v64, s30, v158
	v_cmp_lt_i32_e32 vcc, s53, v64
	s_and_saveexec_b64 s[28:29], vcc
	s_xor_b64 s[28:29], exec, s[28:29]
	v_add_u32_e32 v68, 0xffff0000, v64
	v_mov_b32_e32 v69, v137
	v_lshlrev_b64 v[66:67], 12, v[68:69]
	v_lshrrev_b32_e32 v65, 5, v68
	v_lshl_add_u64 v[66:67], s[16:17], 0, v[66:67]
	v_add_u32_e32 v68, 32, v65
	v_mov_b32_e32 v65, v137
	s_or_saveexec_b64 s[28:29], s[28:29]
	s_ashr_i32 s30, s30, 11
	s_xor_b64 exec, exec, s[28:29]
	v_ashrrev_i32_e32 v65, 31, v64
	v_lshlrev_b64 v[66:67], 12, v[64:65]
	v_lshl_add_u64 v[66:67], s[4:5], 0, v[66:67]
	v_mov_b32_e32 v68, s30
	s_or_b64 exec, exec, s[28:29]
	v_lshlrev_b64 v[70:71], 11, v[64:65]
	v_lshl_add_u64 v[70:71], s[6:7], 0, v[70:71]
	v_lshl_add_u64 v[82:83], v[152:153], 1, v[70:71]
	v_mov_b64_e32 v[74:75], s[18:19]
	v_mad_i64_i32 v[68:69], s[28:29], v68, s54, v[74:75]
	v_lshl_add_u64 v[68:69], v[68:69], 0, v[150:151]
	s_cmpk_lg_i32 s58, 0x100
	s_cbranch_scc1 .Lp10_ng4
	global_load_dwordx4 v[224:227], v[68:69], off
	global_load_dwordx4 v[228:231], v[68:69], off offset:16
	global_load_dwordx4 v[232:235], v[68:69], off offset:128
	global_load_dwordx4 v[236:239], v[68:69], off offset:144
	s_waitcnt vmcnt(0)
.Lp10_ng4:
	v_lshl_add_u64 v[222:223], v[82:83], 0, s[70:71]
	global_load_dwordx4 v[198:201], v[222:223], off
	global_load_dwordx4 v[202:205], v[222:223], off offset:64
	v_lshl_add_u64 v[66:67], v[138:139], 2, v[66:67]
	v_lshl_add_u64 v[66:67], v[140:141], 2, v[66:67]
	v_lshl_add_u64 v[66:67], v[66:67], 0, v[136:137]
	v_lshl_add_u64 v[84:85], v[66:67], 0, v[150:151]
	s_waitcnt vmcnt(13)
	v_lshlrev_b32_e32 v66, 16, v206
	v_and_b32_e32 v67, 0xffff0000, v206
	v_lshlrev_b32_e32 v70, 16, v207
	v_and_b32_e32 v71, 0xffff0000, v207
	v_lshlrev_b32_e32 v86, 16, v208
	v_and_b32_e32 v87, 0xffff0000, v208
	v_lshlrev_b32_e32 v72, 16, v209
	v_and_b32_e32 v73, 0xffff0000, v209
	s_waitcnt vmcnt(31)
	v_pk_fma_f32 v[62:63], v[62:63], v[226:227], v[70:71]
	v_pk_fma_f32 v[60:61], v[60:61], v[224:225], v[66:67]
	s_waitcnt vmcnt(30)
	v_pk_fma_f32 v[58:59], v[58:59], v[230:231], v[72:73]
	v_pk_fma_f32 v[56:57], v[56:57], v[228:229], v[86:87]
	ds_write_b128 v164, v[60:63]
	ds_write_b128 v164, v[56:59] offset:16
	s_waitcnt lgkmcnt(0)
	ds_read_b128 v[56:59], v165
	ds_read_b128 v[60:63], v165 offset:1152
	v_add_co_u32_e32 v70, vcc, s49, v84
	s_nop 1
	v_addc_co_u32_e32 v71, vcc, 0, v85, vcc
	s_waitcnt lgkmcnt(1)
	global_store_dwordx4 v[84:85], v[56:59], off nt
	s_waitcnt lgkmcnt(0)
	global_store_dwordx4 v[70:71], v[60:63], off nt
	s_waitcnt lgkmcnt(0)
	s_nop 0
	s_waitcnt vmcnt(14)
	v_lshlrev_b32_e32 v72, 16, v210
	v_and_b32_e32 v73, 0xffff0000, v210
	v_lshlrev_b32_e32 v56, 16, v211
	v_and_b32_e32 v57, 0xffff0000, v211
	v_lshlrev_b32_e32 v74, 16, v212
	v_and_b32_e32 v75, 0xffff0000, v212
	v_lshlrev_b32_e32 v58, 16, v213
	v_and_b32_e32 v59, 0xffff0000, v213
	s_waitcnt vmcnt(31)
	v_pk_fma_f32 v[54:55], v[54:55], v[234:235], v[56:57]
	v_pk_fma_f32 v[52:53], v[52:53], v[232:233], v[72:73]
	s_waitcnt vmcnt(30)
	v_pk_fma_f32 v[50:51], v[50:51], v[238:239], v[58:59]
	v_pk_fma_f32 v[48:49], v[48:49], v[236:237], v[74:75]
	ds_write_b128 v164, v[52:55]
	ds_write_b128 v164, v[48:51] offset:16
	s_waitcnt lgkmcnt(0)
	ds_read_b128 v[48:51], v165
	ds_read_b128 v[52:55], v165 offset:1152
	s_waitcnt lgkmcnt(1)
	global_store_dwordx4 v[84:85], v[48:51], off offset:128 nt
	s_waitcnt lgkmcnt(0)
	global_store_dwordx4 v[70:71], v[52:55], off offset:128 nt
	s_waitcnt lgkmcnt(0)
	v_or_b32_e32 v50, 16, v64
	v_cmp_lt_i32_e32 vcc, s53, v50
	s_and_saveexec_b64 s[28:29], vcc
	s_xor_b64 s[28:29], exec, s[28:29]
	v_add_u32_e32 v52, 0xffff0010, v64
	v_mov_b32_e32 v53, v137
	v_lshlrev_b64 v[48:49], 12, v[52:53]
	v_lshrrev_b32_e32 v51, 5, v52
	v_lshl_add_u64 v[48:49], s[16:17], 0, v[48:49]
	v_add_u32_e32 v52, 32, v51
	v_mov_b32_e32 v51, v137
	s_andn2_saveexec_b64 s[28:29], s[28:29]
	v_ashrrev_i32_e32 v51, 31, v50
	v_lshlrev_b64 v[48:49], 12, v[50:51]
	v_lshl_add_u64 v[48:49], s[4:5], 0, v[48:49]
	v_mov_b32_e32 v52, s30
	s_or_b64 exec, exec, s[28:29]
	v_lshlrev_b64 v[50:51], 11, v[50:51]
	v_lshl_add_u64 v[50:51], s[6:7], 0, v[50:51]
	v_lshl_add_u64 v[62:63], v[152:153], 1, v[50:51]
	v_mov_b64_e32 v[50:51], s[18:19]
	v_mad_i64_i32 v[50:51], s[28:29], v52, s54, v[50:51]
	v_lshl_add_u64 v[66:67], v[50:51], 0, v[150:151]
	s_cmpk_lg_i32 s58, 0x100
	s_cbranch_scc1 .Lp10_ng5
	global_load_dwordx4 v[224:227], v[66:67], off
	global_load_dwordx4 v[228:231], v[66:67], off offset:16
	global_load_dwordx4 v[232:235], v[66:67], off offset:128
	global_load_dwordx4 v[236:239], v[66:67], off offset:144
	s_waitcnt vmcnt(0)
.Lp10_ng5:
	v_lshl_add_u64 v[222:223], v[62:63], 0, s[70:71]
	global_load_dwordx4 v[206:209], v[222:223], off
	global_load_dwordx4 v[210:213], v[222:223], off offset:64
	v_lshl_add_u64 v[48:49], v[138:139], 2, v[48:49]
	v_lshl_add_u64 v[48:49], v[140:141], 2, v[48:49]
	v_lshl_add_u64 v[48:49], v[48:49], 0, v[136:137]
	v_lshl_add_u64 v[68:69], v[48:49], 0, v[150:151]
	s_waitcnt vmcnt(13)
	v_lshlrev_b32_e32 v48, 16, v214
	v_and_b32_e32 v49, 0xffff0000, v214
	v_lshlrev_b32_e32 v54, 16, v215
	v_and_b32_e32 v55, 0xffff0000, v215
	v_lshlrev_b32_e32 v70, 16, v216
	v_and_b32_e32 v71, 0xffff0000, v216
	v_lshlrev_b32_e32 v56, 16, v217
	v_and_b32_e32 v57, 0xffff0000, v217
	s_waitcnt vmcnt(37)
	v_pk_fma_f32 v[46:47], v[46:47], v[226:227], v[54:55]
	v_pk_fma_f32 v[44:45], v[44:45], v[224:225], v[48:49]
	s_waitcnt vmcnt(36)
	v_pk_fma_f32 v[42:43], v[42:43], v[230:231], v[56:57]
	v_pk_fma_f32 v[40:41], v[40:41], v[228:229], v[70:71]
	ds_write_b128 v164, v[44:47]
	ds_write_b128 v164, v[40:43] offset:16
	s_waitcnt lgkmcnt(0)
	ds_read_b128 v[40:43], v165
	ds_read_b128 v[44:47], v165 offset:1152
	v_add_co_u32_e32 v52, vcc, s49, v68
	s_nop 1
	v_addc_co_u32_e32 v53, vcc, 0, v69, vcc
	s_waitcnt lgkmcnt(1)
	global_store_dwordx4 v[68:69], v[40:43], off nt
	s_waitcnt lgkmcnt(0)
	global_store_dwordx4 v[52:53], v[44:47], off nt
	s_waitcnt lgkmcnt(0)
	s_waitcnt vmcnt(14)
	v_lshlrev_b32_e32 v54, 16, v218
	v_and_b32_e32 v55, 0xffff0000, v218
	v_lshlrev_b32_e32 v40, 16, v219
	v_and_b32_e32 v41, 0xffff0000, v219
	v_lshlrev_b32_e32 v56, 16, v220
	v_and_b32_e32 v57, 0xffff0000, v220
	v_lshlrev_b32_e32 v42, 16, v221
	v_and_b32_e32 v43, 0xffff0000, v221
	s_waitcnt vmcnt(37)
	v_pk_fma_f32 v[38:39], v[38:39], v[234:235], v[40:41]
	v_pk_fma_f32 v[36:37], v[36:37], v[232:233], v[54:55]
	s_waitcnt vmcnt(36)
	v_pk_fma_f32 v[34:35], v[34:35], v[238:239], v[42:43]
	v_pk_fma_f32 v[32:33], v[32:33], v[236:237], v[56:57]
	ds_write_b128 v164, v[36:39]
	ds_write_b128 v164, v[32:35] offset:16
	s_waitcnt lgkmcnt(0)
	ds_read_b128 v[32:35], v165
	ds_read_b128 v[36:39], v165 offset:1152
	s_waitcnt lgkmcnt(1)
	global_store_dwordx4 v[68:69], v[32:35], off offset:128 nt
	s_waitcnt lgkmcnt(0)
	global_store_dwordx4 v[52:53], v[36:39], off offset:128 nt
	s_waitcnt lgkmcnt(0)
	v_or_b32_e32 v34, 32, v64
	v_cmp_lt_i32_e32 vcc, s53, v34
	s_and_saveexec_b64 s[28:29], vcc
	s_xor_b64 s[28:29], exec, s[28:29]
	v_add_u32_e32 v36, 0xffff0020, v64
	v_mov_b32_e32 v37, v137
	v_lshlrev_b64 v[32:33], 12, v[36:37]
	v_lshrrev_b32_e32 v35, 5, v36
	v_lshl_add_u64 v[32:33], s[16:17], 0, v[32:33]
	v_add_u32_e32 v36, 32, v35
	v_mov_b32_e32 v35, v137
	s_andn2_saveexec_b64 s[28:29], s[28:29]
	v_ashrrev_i32_e32 v35, 31, v34
	v_lshlrev_b64 v[32:33], 12, v[34:35]
	v_lshl_add_u64 v[32:33], s[4:5], 0, v[32:33]
	v_mov_b32_e32 v36, s30
	s_or_b64 exec, exec, s[28:29]
	v_lshlrev_b64 v[34:35], 11, v[34:35]
	v_lshl_add_u64 v[34:35], s[6:7], 0, v[34:35]
	v_lshl_add_u64 v[46:47], v[152:153], 1, v[34:35]
	v_mov_b64_e32 v[34:35], s[18:19]
	v_mad_i64_i32 v[34:35], s[28:29], v36, s54, v[34:35]
	v_lshl_add_u64 v[48:49], v[34:35], 0, v[150:151]
	s_cmpk_lg_i32 s58, 0x100
	s_cbranch_scc1 .Lp10_ng6
	global_load_dwordx4 v[224:227], v[48:49], off
	global_load_dwordx4 v[228:231], v[48:49], off offset:16
	global_load_dwordx4 v[232:235], v[48:49], off offset:128
	global_load_dwordx4 v[236:239], v[48:49], off offset:144
	s_waitcnt vmcnt(0)
.Lp10_ng6:
	v_lshl_add_u64 v[32:33], v[138:139], 2, v[32:33]
	v_lshl_add_u64 v[32:33], v[140:141], 2, v[32:33]
	v_lshl_add_u64 v[32:33], v[32:33], 0, v[136:137]
	v_lshl_add_u64 v[50:51], v[32:33], 0, v[150:151]
	s_waitcnt vmcnt(11)
	v_lshlrev_b32_e32 v32, 16, v198
	v_and_b32_e32 v33, 0xffff0000, v198
	v_lshlrev_b32_e32 v38, 16, v199
	v_and_b32_e32 v39, 0xffff0000, v199
	v_lshlrev_b32_e32 v52, 16, v200
	v_and_b32_e32 v53, 0xffff0000, v200
	v_lshlrev_b32_e32 v40, 16, v201
	v_and_b32_e32 v41, 0xffff0000, v201
	s_waitcnt vmcnt(41)
	v_pk_fma_f32 v[30:31], v[30:31], v[226:227], v[38:39]
	v_pk_fma_f32 v[28:29], v[28:29], v[224:225], v[32:33]
	s_waitcnt vmcnt(40)
	v_pk_fma_f32 v[26:27], v[26:27], v[230:231], v[40:41]
	v_pk_fma_f32 v[24:25], v[24:25], v[228:229], v[52:53]
	ds_write_b128 v164, v[28:31]
	ds_write_b128 v164, v[24:27] offset:16
	s_waitcnt lgkmcnt(0)
	ds_read_b128 v[24:27], v165
	ds_read_b128 v[28:31], v165 offset:1152
	v_add_co_u32_e32 v36, vcc, s49, v50
	s_nop 1
	v_addc_co_u32_e32 v37, vcc, 0, v51, vcc
	s_waitcnt lgkmcnt(1)
	global_store_dwordx4 v[50:51], v[24:27], off nt
	s_waitcnt lgkmcnt(0)
	global_store_dwordx4 v[36:37], v[28:31], off nt
	s_waitcnt lgkmcnt(0)
	s_waitcnt vmcnt(12)
	v_lshlrev_b32_e32 v38, 16, v202
	v_and_b32_e32 v39, 0xffff0000, v202
	v_lshlrev_b32_e32 v24, 16, v203
	v_and_b32_e32 v25, 0xffff0000, v203
	v_lshlrev_b32_e32 v40, 16, v204
	v_and_b32_e32 v41, 0xffff0000, v204
	v_lshlrev_b32_e32 v26, 16, v205
	v_and_b32_e32 v27, 0xffff0000, v205
	s_waitcnt vmcnt(41)
	v_pk_fma_f32 v[22:23], v[22:23], v[234:235], v[24:25]
	v_pk_fma_f32 v[20:21], v[20:21], v[232:233], v[38:39]
	s_waitcnt vmcnt(40)
	v_pk_fma_f32 v[18:19], v[18:19], v[238:239], v[26:27]
	v_pk_fma_f32 v[16:17], v[16:17], v[236:237], v[40:41]
	ds_write_b128 v164, v[20:23]
	ds_write_b128 v164, v[16:19] offset:16
	s_waitcnt lgkmcnt(0)
	ds_read_b128 v[16:19], v165
	ds_read_b128 v[20:23], v165 offset:1152
	s_waitcnt lgkmcnt(1)
	global_store_dwordx4 v[50:51], v[16:19], off offset:128 nt
	s_waitcnt lgkmcnt(0)
	global_store_dwordx4 v[36:37], v[20:23], off offset:128 nt
	s_waitcnt lgkmcnt(0)
	v_or_b32_e32 v18, 48, v64
	v_cmp_lt_i32_e32 vcc, s53, v18
	s_and_saveexec_b64 s[28:29], vcc
	s_xor_b64 s[28:29], exec, s[28:29]
	v_add_u32_e32 v20, 0xffff0030, v64
	v_mov_b32_e32 v21, v137
	v_lshlrev_b64 v[16:17], 12, v[20:21]
	v_lshrrev_b32_e32 v19, 5, v20
	v_lshl_add_u64 v[16:17], s[16:17], 0, v[16:17]
	v_add_u32_e32 v20, 32, v19
	v_mov_b32_e32 v19, v137
	s_andn2_saveexec_b64 s[28:29], s[28:29]
	v_ashrrev_i32_e32 v19, 31, v18
	v_lshlrev_b64 v[16:17], 12, v[18:19]
	v_lshl_add_u64 v[16:17], s[4:5], 0, v[16:17]
	v_mov_b32_e32 v20, s30
	s_or_b64 exec, exec, s[28:29]
	v_lshlrev_b64 v[18:19], 11, v[18:19]
	v_lshl_add_u64 v[18:19], s[6:7], 0, v[18:19]
	v_lshl_add_u64 v[30:31], v[152:153], 1, v[18:19]
	v_mov_b64_e32 v[18:19], s[18:19]
	v_mad_i64_i32 v[18:19], s[28:29], v20, s54, v[18:19]
	v_lshl_add_u64 v[32:33], v[18:19], 0, v[150:151]
	s_cmpk_lg_i32 s58, 0x100
	s_cbranch_scc1 .Lp10_ng7
	global_load_dwordx4 v[224:227], v[32:33], off
	global_load_dwordx4 v[228:231], v[32:33], off offset:16
	global_load_dwordx4 v[232:235], v[32:33], off offset:128
	global_load_dwordx4 v[236:239], v[32:33], off offset:144
	s_waitcnt vmcnt(0)
.Lp10_ng7:
	v_lshl_add_u64 v[16:17], v[138:139], 2, v[16:17]
	v_lshl_add_u64 v[16:17], v[140:141], 2, v[16:17]
	v_lshl_add_u64 v[16:17], v[16:17], 0, v[136:137]
	v_lshl_add_u64 v[34:35], v[16:17], 0, v[150:151]
	s_waitcnt vmcnt(9)
	v_lshlrev_b32_e32 v16, 16, v206
	v_and_b32_e32 v17, 0xffff0000, v206
	v_lshlrev_b32_e32 v22, 16, v207
	v_and_b32_e32 v23, 0xffff0000, v207
	v_lshlrev_b32_e32 v36, 16, v208
	v_and_b32_e32 v37, 0xffff0000, v208
	v_lshlrev_b32_e32 v24, 16, v209
	v_and_b32_e32 v25, 0xffff0000, v209
	s_waitcnt vmcnt(45)
	v_pk_fma_f32 v[14:15], v[14:15], v[226:227], v[22:23]
	v_pk_fma_f32 v[12:13], v[12:13], v[224:225], v[16:17]
	s_waitcnt vmcnt(44)
	v_pk_fma_f32 v[10:11], v[10:11], v[230:231], v[24:25]
	v_pk_fma_f32 v[8:9], v[8:9], v[228:229], v[36:37]
	ds_write_b128 v164, v[12:15]
	ds_write_b128 v164, v[8:11] offset:16
	s_waitcnt lgkmcnt(0)
	ds_read_b128 v[8:11], v165
	ds_read_b128 v[12:15], v165 offset:1152
	v_add_co_u32_e32 v20, vcc, s49, v34
	s_nop 1
	v_addc_co_u32_e32 v21, vcc, 0, v35, vcc
	s_waitcnt lgkmcnt(1)
	global_store_dwordx4 v[34:35], v[8:11], off nt
	s_waitcnt lgkmcnt(0)
	global_store_dwordx4 v[20:21], v[12:15], off nt
	s_waitcnt lgkmcnt(0)
	s_and_b64 vcc, exec, s[0:1]
	s_mov_b64 s[0:1], -1
	s_waitcnt vmcnt(10)
	v_lshlrev_b32_e32 v22, 16, v210
	v_and_b32_e32 v23, 0xffff0000, v210
	v_lshlrev_b32_e32 v8, 16, v211
	v_and_b32_e32 v9, 0xffff0000, v211
	v_lshlrev_b32_e32 v24, 16, v212
	v_and_b32_e32 v25, 0xffff0000, v212
	v_lshlrev_b32_e32 v10, 16, v213
	v_and_b32_e32 v11, 0xffff0000, v213
	s_waitcnt vmcnt(45)
	v_pk_fma_f32 v[6:7], v[6:7], v[234:235], v[8:9]
	v_pk_fma_f32 v[4:5], v[4:5], v[232:233], v[22:23]
	s_waitcnt vmcnt(44)
	v_pk_fma_f32 v[2:3], v[2:3], v[238:239], v[10:11]
	v_pk_fma_f32 v[0:1], v[0:1], v[236:237], v[24:25]
	ds_write_b128 v164, v[4:7]
	ds_write_b128 v164, v[0:3] offset:16
	s_waitcnt lgkmcnt(0)
	ds_read_b128 v[0:3], v165
	ds_read_b128 v[4:7], v165 offset:1152
	s_waitcnt lgkmcnt(1)
	global_store_dwordx4 v[34:35], v[0:3], off offset:128 nt
	s_waitcnt lgkmcnt(0)
	global_store_dwordx4 v[20:21], v[4:7], off offset:128 nt
	s_waitcnt lgkmcnt(0)
	s_cbranch_vccnz .LBB0_1520
	s_andn2_b64 vcc, exec, s[14:15]
	s_cbranch_vccnz .LBB0_1519
	s_barrier
	s_branch .LBB0_1519
